# K-loops: lower wave priority after the end-of-MMA barrier instead of before it (MMA wave arrives at the hand-off barrier one issue slot earlier)
# baseline (speedup 1.0000x reference)
; #define PG8_STAGE(bufoff, gbase, voff) do { _Pragma("unroll") for (int _i = 0; _i < 2; ++_i) \
;         __builtin_amdgcn_global_load_lds((const unsigned*)((const char*)(gbase) + (voff)[_i]), (PG8_LAS unsigned*)(lds + (bufoff) + ldsw + _i * 8192), 16, 0, 0); } while (0)
; #define PG8_LDA(dst, b, h) do { _Pragma("unroll") for (int m = 0; m < 4; ++m) _Pragma("unroll") for (int k = 0; k < 2; ++k) dst[m][k] = *(const PG8_LAS bf16x8*)(lds + PG8_SA(b, h) + aoff + m * 2048 + k * 1024); } while (0)
; #define PG8_LDB(dst, b, h) do { _Pragma("unroll") for (int n = 0; n < 2; ++n) _Pragma("unroll") for (int k = 0; k < 2; ++k) dst[n][k] = *(const PG8_LAS bf16x8*)(lds + PG8_SB(b, h) + boff + n * 2048 + k * 1024); } while (0)
; #define PG8_MMA(ai, bj, At, Bt) do { __builtin_amdgcn_s_setprio(1); _Pragma("unroll") for (int m = 0; m < 4; ++m) _Pragma("unroll") for (int n = 0; n < 2; ++n) _Pragma("unroll") for (int k = 0; k < 2; ++k) \
;         acc[ai][bj][m][n] = __builtin_amdgcn_mfma_f32_16x16x32_bf16(Bt[n][k], At[m][k], acc[ai][bj][m][n], 0, 0, 0); __builtin_amdgcn_s_setprio(0); } while (0)
; #define PG8_WAIT_V(n) asm volatile("s_waitcnt vmcnt(" #n ")" ::: "memory")
; #define PG8_WAIT_L(n) asm volatile("s_waitcnt lgkmcnt(" #n ")" ::: "memory")
; template <class Epi, class Sched, bool ALIGN_EPI = false, bool SP2 = false>
; __device__ __forceinline__ void gemm_phase(PG8_LAS unsigned char* lds, const Gemm g, const Sched& S, const Epi& E) {
;     ...
;             const bool last = (t == nt - 2);
;             const char* a1 = cA + (size_t)(t + 1) * kstep;
;             const char* a2 = last ? nA : cA + (size_t)(t + 2) * kstep; const char* b2 = last ? nB : cB + (size_t)(t + 2) * kstep;
;             const char* a3 = a2 + kstep; const char* b3 = b2 + kstep;
;             if (last && has_next) S.a_ready(nxt);
;             if constexpr (SP2) {
;             PG8_LDB(B0, 0, 0); PG8_LDB(B1, 0, 1); PG8_SCHED; PG8_LDA(At, 0, 0); PG8_STAGE(PG8_SA(1, 1), a1 + hstep, voffA);
;             PG8_WAIT_V(8); PG8_WAIT_L(0); PG8_BAR; PG8_MMA(0, 0, At, B0); PG8_MMA(0, 1, At, B1); PG8_BAR; PG8_SCHED;
;             PG8_LDA(At, 0, 1); PG8_STAGE(PG8_SB(0, 0), b2, voffB); PG8_STAGE(PG8_SB(0, 1), b2 + hstep, voffB); PG8_STAGE(PG8_SA(0, 0), a2, voffA);
;             PG8_WAIT_V(8); PG8_WAIT_L(0); PG8_BAR; PG8_MMA(1, 0, At, B0); PG8_MMA(1, 1, At, B1); PG8_BAR; PG8_SCHED;
.LBB0_57:
	s_add_u32 s46, s44, 0xfff80080
	s_addc_u32 s47, s45, -1
	s_add_i32 s57, 0, 0x10000
	s_cmp_eq_u32 s56, 28
	s_cselect_b32 s49, s17, s47
	s_cselect_b32 s48, s25, s46
	v_add_u32_e32 v148, s57, v151
	s_cselect_b32 s47, s15, s55
	s_cselect_b32 s46, s43, s54
	s_add_i32 s60, 0, 0x14000
	ds_read_b128 v[140:143], v148
	ds_read_b128 v[144:147], v148 offset:1024
	ds_read_b128 v[174:177], v148 offset:2048
	ds_read_b128 v[178:181], v148 offset:3072
	v_add_u32_e32 v148, s60, v151
	ds_read_b128 v[182:185], v148
	ds_read_b128 v[186:189], v148 offset:1024
	ds_read_b128 v[190:193], v148 offset:2048
	ds_read_b128 v[194:197], v148 offset:3072
	v_lshl_add_u64 v[148:149], s[44:45], 0, v[136:137]
	s_add_i32 m0, s28, 0xc000
	ds_read_b128 v[198:201], v172
	ds_read_b128 v[202:205], v172 offset:1024
	ds_read_b128 v[206:209], v172 offset:2048
	ds_read_b128 v[210:213], v172 offset:3072
	ds_read_b128 v[220:223], v172 offset:4096
	ds_read_b128 v[224:227], v172 offset:5120
	ds_read_b128 v[228:231], v172 offset:6144
	ds_read_b128 v[232:235], v172 offset:7168
	global_load_lds_dwordx4 v[148:149], off
	v_lshl_add_u64 v[148:149], s[44:45], 0, v[138:139]
	s_add_i32 m0, s28, 0xe000
	s_nop 0
	global_load_lds_dwordx4 v[148:149], off
	s_waitcnt vmcnt(8)
	s_waitcnt lgkmcnt(0)
	s_setprio 1
	s_barrier
	v_mfma_f32_16x16x32_bf16 v[124:127], v[140:143], v[198:201], v[124:127]
	v_mfma_f32_16x16x32_bf16 v[120:123], v[174:177], v[198:201], v[120:123]
	v_mfma_f32_16x16x32_bf16 v[116:119], v[140:143], v[206:209], v[116:119]
	v_mfma_f32_16x16x32_bf16 v[112:115], v[174:177], v[206:209], v[112:115]
	v_mfma_f32_16x16x32_bf16 v[100:103], v[140:143], v[220:223], v[100:103]
	v_mfma_f32_16x16x32_bf16 v[96:99], v[174:177], v[220:223], v[96:99]
	v_mfma_f32_16x16x32_bf16 v[84:87], v[140:143], v[228:231], v[84:87]
	v_mfma_f32_16x16x32_bf16 v[80:83], v[174:177], v[228:231], v[80:83]
	v_mfma_f32_16x16x32_bf16 v[124:127], v[144:147], v[202:205], v[124:127]
	v_mfma_f32_16x16x32_bf16 v[120:123], v[178:181], v[202:205], v[120:123]
	v_mfma_f32_16x16x32_bf16 v[116:119], v[144:147], v[210:213], v[116:119]
	v_mfma_f32_16x16x32_bf16 v[112:115], v[178:181], v[210:213], v[112:115]
	v_mfma_f32_16x16x32_bf16 v[100:103], v[144:147], v[224:227], v[100:103]
	v_mfma_f32_16x16x32_bf16 v[96:99], v[178:181], v[224:227], v[96:99]
	v_mfma_f32_16x16x32_bf16 v[84:87], v[144:147], v[232:235], v[84:87]
	v_mfma_f32_16x16x32_bf16 v[80:83], v[178:181], v[232:235], v[80:83]
	v_mfma_f32_16x16x32_bf16 v[108:111], v[182:185], v[198:201], v[108:111]
	v_mfma_f32_16x16x32_bf16 v[104:107], v[190:193], v[198:201], v[104:107]
	v_mfma_f32_16x16x32_bf16 v[92:95], v[182:185], v[206:209], v[92:95]
	v_mfma_f32_16x16x32_bf16 v[88:91], v[190:193], v[206:209], v[88:91]
	v_mfma_f32_16x16x32_bf16 v[76:79], v[182:185], v[220:223], v[76:79]
	v_mfma_f32_16x16x32_bf16 v[72:75], v[190:193], v[220:223], v[72:75]
	v_mfma_f32_16x16x32_bf16 v[68:71], v[182:185], v[228:231], v[68:71]
	v_mfma_f32_16x16x32_bf16 v[64:67], v[190:193], v[228:231], v[64:67]
	v_mfma_f32_16x16x32_bf16 v[108:111], v[186:189], v[202:205], v[108:111]
	v_mfma_f32_16x16x32_bf16 v[104:107], v[194:197], v[202:205], v[104:107]
	v_mfma_f32_16x16x32_bf16 v[92:95], v[186:189], v[210:213], v[92:95]
	v_mfma_f32_16x16x32_bf16 v[88:91], v[194:197], v[210:213], v[88:91]
	v_mfma_f32_16x16x32_bf16 v[76:79], v[186:189], v[224:227], v[76:79]
	v_mfma_f32_16x16x32_bf16 v[72:75], v[194:197], v[224:227], v[72:75]
	v_mfma_f32_16x16x32_bf16 v[68:71], v[186:189], v[232:235], v[68:71]
	v_mfma_f32_16x16x32_bf16 v[64:67], v[194:197], v[232:235], v[64:67]
	s_barrier
	s_setprio 0
	s_add_i32 s57, s57, s26
	v_lshl_add_u64 v[148:149], s[46:47], 0, v[132:133]
	s_mov_b32 m0, s57
	ds_read_b128 v[198:201], v172 offset:16384
	ds_read_b128 v[202:205], v172 offset:17408
	ds_read_b128 v[206:209], v172 offset:18432
	ds_read_b128 v[210:213], v172 offset:19456
	ds_read_b128 v[220:223], v172 offset:20480
	ds_read_b128 v[224:227], v172 offset:21504
	ds_read_b128 v[228:231], v172 offset:22528
	ds_read_b128 v[232:235], v172 offset:23552
	global_load_lds_dwordx4 v[148:149], off
	s_add_i32 m0, s57, 0x2000
	s_add_u32 s58, s46, 0x80000
	v_lshl_add_u64 v[214:215], s[46:47], 0, v[128:129]
	s_addc_u32 s59, s47, 0
	s_add_i32 s57, s60, s26
	global_load_lds_dwordx4 v[214:215], off
	v_lshl_add_u64 v[236:237], s[58:59], 0, v[132:133]
	s_mov_b32 m0, s57
	v_lshl_add_u64 v[238:239], s[48:49], 0, v[130:131]
	global_load_lds_dwordx4 v[236:237], off
	v_lshl_add_u64 v[236:237], s[58:59], 0, v[128:129]
	s_add_i32 m0, s57, 0x2000
	s_nop 0
	global_load_lds_dwordx4 v[236:237], off
	v_lshl_add_u64 v[236:237], s[48:49], 0, v[134:135]
	s_mov_b32 m0, s28
	s_nop 0
	global_load_lds_dwordx4 v[236:237], off
	s_mov_b32 m0, s29
	s_nop 0
	global_load_lds_dwordx4 v[238:239], off
	s_waitcnt vmcnt(8)
	s_waitcnt lgkmcnt(0)
	s_setprio 1
	s_barrier
; #define PG8_STAGE(bufoff, gbase, voff) do { _Pragma("unroll") for (int _i = 0; _i < 2; ++_i) \
;         __builtin_amdgcn_global_load_lds((const unsigned*)((const char*)(gbase) + (voff)[_i]), (PG8_LAS unsigned*)(lds + (bufoff) + ldsw + _i * 8192), 16, 0, 0); } while (0)
; #define PG8_LDA(dst, b, h) do { _Pragma("unroll") for (int m = 0; m < 4; ++m) _Pragma("unroll") for (int k = 0; k < 2; ++k) dst[m][k] = *(const PG8_LAS bf16x8*)(lds + PG8_SA(b, h) + aoff + m * 2048 + k * 1024); } while (0)
; #define PG8_LDB(dst, b, h) do { _Pragma("unroll") for (int n = 0; n < 2; ++n) _Pragma("unroll") for (int k = 0; k < 2; ++k) dst[n][k] = *(const PG8_LAS bf16x8*)(lds + PG8_SB(b, h) + boff + n * 2048 + k * 1024); } while (0)
; #define PG8_MMA(ai, bj, At, Bt) do { __builtin_amdgcn_s_setprio(1); _Pragma("unroll") for (int m = 0; m < 4; ++m) _Pragma("unroll") for (int n = 0; n < 2; ++n) _Pragma("unroll") for (int k = 0; k < 2; ++k) \
;         acc[ai][bj][m][n] = __builtin_amdgcn_mfma_f32_16x16x32_bf16(Bt[n][k], At[m][k], acc[ai][bj][m][n], 0, 0, 0); __builtin_amdgcn_s_setprio(0); } while (0)
; #define PG8_WAIT_V(n) asm volatile("s_waitcnt vmcnt(" #n ")" ::: "memory")
; #define PG8_WAIT_L(n) asm volatile("s_waitcnt lgkmcnt(" #n ")" ::: "memory")
; #define PG8_BAR __builtin_amdgcn_s_barrier()
; #define PG8_SCHED __builtin_amdgcn_sched_barrier(0)
; template <class Epi, class Sched, bool ALIGN_EPI = false, bool SP2 = false>
; __device__ __forceinline__ void gemm_phase(PG8_LAS unsigned char* lds, const Gemm g, const Sched& S, const Epi& E) {
;     ...
;             PG8_WAIT_V(8); PG8_WAIT_L(0); PG8_BAR; PG8_MMA(1, 0, At, B0); PG8_MMA(1, 1, At, B1); PG8_BAR; PG8_SCHED;
;             PG8_LDB(B0, 1, 0); PG8_LDB(B1, 1, 1); PG8_SCHED; PG8_LDA(At, 1, 0); PG8_STAGE(PG8_SA(0, 1), a2 + hstep, voffA);
;             PG8_WAIT_V(8); PG8_WAIT_L(0); PG8_BAR; PG8_MMA(0, 0, At, B0); PG8_MMA(0, 1, At, B1); PG8_BAR; PG8_SCHED;
	v_mfma_f32_16x16x32_bf16 v[60:63], v[140:143], v[198:201], v[60:63]
	v_mfma_f32_16x16x32_bf16 v[56:59], v[174:177], v[198:201], v[56:59]
	v_mfma_f32_16x16x32_bf16 v[52:55], v[140:143], v[206:209], v[52:55]
	v_mfma_f32_16x16x32_bf16 v[48:51], v[174:177], v[206:209], v[48:51]
	v_mfma_f32_16x16x32_bf16 v[36:39], v[140:143], v[220:223], v[36:39]
	v_mfma_f32_16x16x32_bf16 v[32:35], v[174:177], v[220:223], v[32:35]
	v_mfma_f32_16x16x32_bf16 v[20:23], v[140:143], v[228:231], v[20:23]
	v_mfma_f32_16x16x32_bf16 v[16:19], v[174:177], v[228:231], v[16:19]
	v_mfma_f32_16x16x32_bf16 v[60:63], v[144:147], v[202:205], v[60:63]
	v_mfma_f32_16x16x32_bf16 v[56:59], v[178:181], v[202:205], v[56:59]
	v_mfma_f32_16x16x32_bf16 v[52:55], v[144:147], v[210:213], v[52:55]
	v_mfma_f32_16x16x32_bf16 v[48:51], v[178:181], v[210:213], v[48:51]
	v_mfma_f32_16x16x32_bf16 v[36:39], v[144:147], v[224:227], v[36:39]
	v_mfma_f32_16x16x32_bf16 v[32:35], v[178:181], v[224:227], v[32:35]
	v_mfma_f32_16x16x32_bf16 v[20:23], v[144:147], v[232:235], v[20:23]
	v_mfma_f32_16x16x32_bf16 v[16:19], v[178:181], v[232:235], v[16:19]
	v_mfma_f32_16x16x32_bf16 v[44:47], v[182:185], v[198:201], v[44:47]
	v_mfma_f32_16x16x32_bf16 v[40:43], v[190:193], v[198:201], v[40:43]
	v_mfma_f32_16x16x32_bf16 v[28:31], v[182:185], v[206:209], v[28:31]
	v_mfma_f32_16x16x32_bf16 v[24:27], v[190:193], v[206:209], v[24:27]
	v_mfma_f32_16x16x32_bf16 v[12:15], v[182:185], v[220:223], v[12:15]
	v_mfma_f32_16x16x32_bf16 v[8:11], v[190:193], v[220:223], v[8:11]
	v_mfma_f32_16x16x32_bf16 v[4:7], v[182:185], v[228:231], v[4:7]
	v_mfma_f32_16x16x32_bf16 v[0:3], v[190:193], v[228:231], v[0:3]
	v_mfma_f32_16x16x32_bf16 v[44:47], v[186:189], v[202:205], v[44:47]
	v_mfma_f32_16x16x32_bf16 v[40:43], v[194:197], v[202:205], v[40:43]
	v_mfma_f32_16x16x32_bf16 v[28:31], v[186:189], v[210:213], v[28:31]
	v_mfma_f32_16x16x32_bf16 v[24:27], v[194:197], v[210:213], v[24:27]
	v_mfma_f32_16x16x32_bf16 v[12:15], v[186:189], v[224:227], v[12:15]
	v_mfma_f32_16x16x32_bf16 v[8:11], v[194:197], v[224:227], v[8:11]
	v_mfma_f32_16x16x32_bf16 v[4:7], v[186:189], v[232:235], v[4:7]
	v_mfma_f32_16x16x32_bf16 v[0:3], v[194:197], v[232:235], v[0:3]
	s_barrier
	s_setprio 0
	s_add_i32 s57, 0, 0x18000
	v_add_u32_e32 v152, s57, v151
	s_add_i32 s58, 0, 0x1c000
	ds_read_b128 v[140:143], v152
	ds_read_b128 v[144:147], v152 offset:1024
	ds_read_b128 v[174:177], v152 offset:2048
	ds_read_b128 v[178:181], v152 offset:3072
	v_add_u32_e32 v152, s58, v151
	ds_read_b128 v[182:185], v152
	ds_read_b128 v[186:189], v152 offset:1024
	ds_read_b128 v[190:193], v152 offset:2048
	ds_read_b128 v[194:197], v152 offset:3072
	s_add_u32 s48, s48, 0x80000
	s_addc_u32 s49, s49, 0
	s_mov_b32 m0, s33
	v_lshl_add_u64 v[240:241], s[48:49], 0, v[134:135]
	ds_read_b128 v[198:201], v172 offset:32768
	ds_read_b128 v[202:205], v172 offset:33792
	ds_read_b128 v[206:209], v172 offset:34816
	ds_read_b128 v[210:213], v172 offset:35840
	ds_read_b128 v[220:223], v172 offset:36864
	ds_read_b128 v[224:227], v172 offset:37888
	ds_read_b128 v[228:231], v172 offset:38912
	ds_read_b128 v[232:235], v172 offset:39936
	global_load_lds_dwordx4 v[240:241], off
	v_lshl_add_u64 v[240:241], s[48:49], 0, v[130:131]
	s_mov_b32 m0, s50
	s_nop 0
	global_load_lds_dwordx4 v[240:241], off
	s_waitcnt vmcnt(8)
	s_waitcnt lgkmcnt(0)
	s_setprio 1
	s_barrier
	v_mfma_f32_16x16x32_bf16 v[124:127], v[140:143], v[198:201], v[124:127]
	v_mfma_f32_16x16x32_bf16 v[120:123], v[174:177], v[198:201], v[120:123]
	v_mfma_f32_16x16x32_bf16 v[116:119], v[140:143], v[206:209], v[116:119]
	v_mfma_f32_16x16x32_bf16 v[112:115], v[174:177], v[206:209], v[112:115]
	v_mfma_f32_16x16x32_bf16 v[100:103], v[140:143], v[220:223], v[100:103]
	v_mfma_f32_16x16x32_bf16 v[96:99], v[174:177], v[220:223], v[96:99]
	v_mfma_f32_16x16x32_bf16 v[84:87], v[140:143], v[228:231], v[84:87]
	v_mfma_f32_16x16x32_bf16 v[80:83], v[174:177], v[228:231], v[80:83]
	v_mfma_f32_16x16x32_bf16 v[124:127], v[144:147], v[202:205], v[124:127]
	v_mfma_f32_16x16x32_bf16 v[120:123], v[178:181], v[202:205], v[120:123]
	v_mfma_f32_16x16x32_bf16 v[116:119], v[144:147], v[210:213], v[116:119]
	v_mfma_f32_16x16x32_bf16 v[112:115], v[178:181], v[210:213], v[112:115]
	v_mfma_f32_16x16x32_bf16 v[100:103], v[144:147], v[224:227], v[100:103]
	v_mfma_f32_16x16x32_bf16 v[96:99], v[178:181], v[224:227], v[96:99]
	v_mfma_f32_16x16x32_bf16 v[84:87], v[144:147], v[232:235], v[84:87]
	v_mfma_f32_16x16x32_bf16 v[80:83], v[178:181], v[232:235], v[80:83]
	v_mfma_f32_16x16x32_bf16 v[108:111], v[182:185], v[198:201], v[108:111]
	v_mfma_f32_16x16x32_bf16 v[104:107], v[190:193], v[198:201], v[104:107]
	v_mfma_f32_16x16x32_bf16 v[92:95], v[182:185], v[206:209], v[92:95]
	v_mfma_f32_16x16x32_bf16 v[88:91], v[190:193], v[206:209], v[88:91]
	v_mfma_f32_16x16x32_bf16 v[76:79], v[182:185], v[220:223], v[76:79]
	v_mfma_f32_16x16x32_bf16 v[72:75], v[190:193], v[220:223], v[72:75]
	v_mfma_f32_16x16x32_bf16 v[68:71], v[182:185], v[228:231], v[68:71]
	v_mfma_f32_16x16x32_bf16 v[64:67], v[190:193], v[228:231], v[64:67]
	v_mfma_f32_16x16x32_bf16 v[108:111], v[186:189], v[202:205], v[108:111]
	v_mfma_f32_16x16x32_bf16 v[104:107], v[194:197], v[202:205], v[104:107]
	v_mfma_f32_16x16x32_bf16 v[92:95], v[186:189], v[210:213], v[92:95]
	v_mfma_f32_16x16x32_bf16 v[88:91], v[194:197], v[210:213], v[88:91]
	v_mfma_f32_16x16x32_bf16 v[76:79], v[186:189], v[224:227], v[76:79]
	v_mfma_f32_16x16x32_bf16 v[72:75], v[194:197], v[224:227], v[72:75]
	v_mfma_f32_16x16x32_bf16 v[68:71], v[186:189], v[232:235], v[68:71]
	v_mfma_f32_16x16x32_bf16 v[64:67], v[194:197], v[232:235], v[64:67]
	s_barrier
; #define PG8_STAGE(bufoff, gbase, voff) do { _Pragma("unroll") for (int _i = 0; _i < 2; ++_i) \
;         __builtin_amdgcn_global_load_lds((const unsigned*)((const char*)(gbase) + (voff)[_i]), (PG8_LAS unsigned*)(lds + (bufoff) + ldsw + _i * 8192), 16, 0, 0); } while (0)
; #define PG8_LDA(dst, b, h) do { _Pragma("unroll") for (int m = 0; m < 4; ++m) _Pragma("unroll") for (int k = 0; k < 2; ++k) dst[m][k] = *(const PG8_LAS bf16x8*)(lds + PG8_SA(b, h) + aoff + m * 2048 + k * 1024); } while (0)
; #define PG8_MMA(ai, bj, At, Bt) do { __builtin_amdgcn_s_setprio(1); _Pragma("unroll") for (int m = 0; m < 4; ++m) _Pragma("unroll") for (int n = 0; n < 2; ++n) _Pragma("unroll") for (int k = 0; k < 2; ++k) \
;         acc[ai][bj][m][n] = __builtin_amdgcn_mfma_f32_16x16x32_bf16(Bt[n][k], At[m][k], acc[ai][bj][m][n], 0, 0, 0); __builtin_amdgcn_s_setprio(0); } while (0)
; #define PG8_WAIT_V(n) asm volatile("s_waitcnt vmcnt(" #n ")" ::: "memory")
; #define PG8_WAIT_L(n) asm volatile("s_waitcnt lgkmcnt(" #n ")" ::: "memory")
; #define PG8_BAR __builtin_amdgcn_s_barrier()
; #define PG8_SCHED __builtin_amdgcn_sched_barrier(0)
; template <class Epi, class Sched, bool ALIGN_EPI = false, bool SP2 = false>
; __device__ __forceinline__ void gemm_phase(PG8_LAS unsigned char* lds, const Gemm g, const Sched& S, const Epi& E) {
;     ...
;             PG8_LDA(At, 1, 1); PG8_STAGE(PG8_SB(1, 0), b3, voffB); PG8_STAGE(PG8_SB(1, 1), b3 + hstep, voffB); PG8_STAGE(PG8_SA(1, 0), a3, voffA);
;             PG8_WAIT_V(8); PG8_WAIT_L(0); PG8_BAR; PG8_MMA(1, 0, At, B0); PG8_MMA(1, 1, At, B1); PG8_BAR; PG8_SCHED;
	s_setprio 0
	s_add_i32 s48, s57, s26
	v_lshl_add_u64 v[148:149], v[148:149], 0, s[90:91]
	s_mov_b32 m0, s48
	ds_read_b128 v[198:201], v172 offset:49152
	ds_read_b128 v[202:205], v172 offset:50176
	ds_read_b128 v[206:209], v172 offset:51200
	ds_read_b128 v[210:213], v172 offset:52224
	ds_read_b128 v[220:223], v172 offset:53248
	ds_read_b128 v[224:227], v172 offset:54272
	ds_read_b128 v[228:231], v172 offset:55296
	ds_read_b128 v[232:235], v172 offset:56320
	global_load_lds_dwordx4 v[148:149], off
	s_add_i32 m0, s48, 0x2000
	s_add_u32 s46, s46, 0x80080
	v_lshl_add_u64 v[148:149], v[214:215], 0, s[90:91]
	s_addc_u32 s47, s47, 0
	s_add_i32 s48, s58, s26
	global_load_lds_dwordx4 v[148:149], off
	v_lshl_add_u64 v[148:149], s[46:47], 0, v[132:133]
	s_mov_b32 m0, s48
	s_nop 0
	global_load_lds_dwordx4 v[148:149], off
	v_lshl_add_u64 v[148:149], s[46:47], 0, v[128:129]
	s_add_i32 m0, s48, 0x2000
	s_nop 0
	global_load_lds_dwordx4 v[148:149], off
	v_lshl_add_u64 v[148:149], v[236:237], 0, s[90:91]
	s_mov_b32 m0, s4
	s_nop 0
	global_load_lds_dwordx4 v[148:149], off
	v_lshl_add_u64 v[148:149], v[238:239], 0, s[90:91]
	s_mov_b32 m0, s51
	s_nop 0
	global_load_lds_dwordx4 v[148:149], off
	s_waitcnt vmcnt(8)
	s_waitcnt lgkmcnt(0)
	s_setprio 1
	s_barrier
	v_mfma_f32_16x16x32_bf16 v[60:63], v[140:143], v[198:201], v[60:63]
	v_mfma_f32_16x16x32_bf16 v[56:59], v[174:177], v[198:201], v[56:59]
	v_mfma_f32_16x16x32_bf16 v[52:55], v[140:143], v[206:209], v[52:55]
	v_mfma_f32_16x16x32_bf16 v[48:51], v[174:177], v[206:209], v[48:51]
	v_mfma_f32_16x16x32_bf16 v[36:39], v[140:143], v[220:223], v[36:39]
	v_mfma_f32_16x16x32_bf16 v[32:35], v[174:177], v[220:223], v[32:35]
	v_mfma_f32_16x16x32_bf16 v[20:23], v[140:143], v[228:231], v[20:23]
	v_mfma_f32_16x16x32_bf16 v[16:19], v[174:177], v[228:231], v[16:19]
	v_mfma_f32_16x16x32_bf16 v[60:63], v[144:147], v[202:205], v[60:63]
	v_mfma_f32_16x16x32_bf16 v[56:59], v[178:181], v[202:205], v[56:59]
	v_mfma_f32_16x16x32_bf16 v[52:55], v[144:147], v[210:213], v[52:55]
	v_mfma_f32_16x16x32_bf16 v[48:51], v[178:181], v[210:213], v[48:51]
	v_mfma_f32_16x16x32_bf16 v[36:39], v[144:147], v[224:227], v[36:39]
	v_mfma_f32_16x16x32_bf16 v[32:35], v[178:181], v[224:227], v[32:35]
	v_mfma_f32_16x16x32_bf16 v[20:23], v[144:147], v[232:235], v[20:23]
	v_mfma_f32_16x16x32_bf16 v[16:19], v[178:181], v[232:235], v[16:19]
	v_mfma_f32_16x16x32_bf16 v[44:47], v[182:185], v[198:201], v[44:47]
	v_mfma_f32_16x16x32_bf16 v[40:43], v[190:193], v[198:201], v[40:43]
	v_mfma_f32_16x16x32_bf16 v[28:31], v[182:185], v[206:209], v[28:31]
	v_mfma_f32_16x16x32_bf16 v[24:27], v[190:193], v[206:209], v[24:27]
	v_mfma_f32_16x16x32_bf16 v[12:15], v[182:185], v[220:223], v[12:15]
	v_mfma_f32_16x16x32_bf16 v[8:11], v[190:193], v[220:223], v[8:11]
	v_mfma_f32_16x16x32_bf16 v[4:7], v[182:185], v[228:231], v[4:7]
	v_mfma_f32_16x16x32_bf16 v[0:3], v[190:193], v[228:231], v[0:3]
	v_mfma_f32_16x16x32_bf16 v[44:47], v[186:189], v[202:205], v[44:47]
	v_mfma_f32_16x16x32_bf16 v[40:43], v[194:197], v[202:205], v[40:43]
	v_mfma_f32_16x16x32_bf16 v[28:31], v[186:189], v[210:213], v[28:31]
	v_mfma_f32_16x16x32_bf16 v[24:27], v[194:197], v[210:213], v[24:27]
	v_mfma_f32_16x16x32_bf16 v[12:15], v[186:189], v[224:227], v[12:15]
	v_mfma_f32_16x16x32_bf16 v[8:11], v[194:197], v[224:227], v[8:11]
	v_mfma_f32_16x16x32_bf16 v[4:7], v[186:189], v[232:235], v[4:7]
	v_mfma_f32_16x16x32_bf16 v[0:3], v[194:197], v[232:235], v[0:3]
	s_barrier
	s_setprio 0
	s_add_i32 s56, s56, 2
	s_add_u32 s44, s44, 0x100
	s_addc_u32 s45, s45, 0
	s_add_u32 s54, s54, 0x100
	s_addc_u32 s55, s55, 0
	s_cmp_gt_u32 s56, 29
	s_cbranch_scc0 .LBB0_57
	s_and_b64 vcc, exec, s[12:13]
	s_cbranch_vccz .LBB0_60
	s_barrier

; #define PG8_STAGE(bufoff, gbase, voff) do { _Pragma("unroll") for (int _i = 0; _i < 2; ++_i) \
;         __builtin_amdgcn_global_load_lds((const unsigned*)((const char*)(gbase) + (voff)[_i]), (PG8_LAS unsigned*)(lds + (bufoff) + ldsw + _i * 8192), 16, 0, 0); } while (0)
; #define PG8_LDA(dst, b, h) do { _Pragma("unroll") for (int m = 0; m < 4; ++m) _Pragma("unroll") for (int k = 0; k < 2; ++k) dst[m][k] = *(const PG8_LAS bf16x8*)(lds + PG8_SA(b, h) + aoff + m * 2048 + k * 1024); } while (0)
; #define PG8_LDB(dst, b, h) do { _Pragma("unroll") for (int n = 0; n < 2; ++n) _Pragma("unroll") for (int k = 0; k < 2; ++k) dst[n][k] = *(const PG8_LAS bf16x8*)(lds + PG8_SB(b, h) + boff + n * 2048 + k * 1024); } while (0)
; #define PG8_MMA(ai, bj, At, Bt) do { __builtin_amdgcn_s_setprio(1); _Pragma("unroll") for (int m = 0; m < 4; ++m) _Pragma("unroll") for (int n = 0; n < 2; ++n) _Pragma("unroll") for (int k = 0; k < 2; ++k) \
;         acc[ai][bj][m][n] = __builtin_amdgcn_mfma_f32_16x16x32_bf16(Bt[n][k], At[m][k], acc[ai][bj][m][n], 0, 0, 0); __builtin_amdgcn_s_setprio(0); } while (0)
; #define PG8_WAIT_V(n) asm volatile("s_waitcnt vmcnt(" #n ")" ::: "memory")
; #define PG8_WAIT_L(n) asm volatile("s_waitcnt lgkmcnt(" #n ")" ::: "memory")
; template <class Epi, class Sched, bool ALIGN_EPI = false, bool SP2 = false>
; __device__ __forceinline__ void gemm_phase(PG8_LAS unsigned char* lds, const Gemm g, const Sched& S, const Epi& E) {
;     ...
;             const bool last = (t == nt - 2);
;             const char* a1 = cA + (size_t)(t + 1) * kstep;
;             const char* a2 = last ? nA : cA + (size_t)(t + 2) * kstep; const char* b2 = last ? nB : cB + (size_t)(t + 2) * kstep;
;             const char* a3 = a2 + kstep; const char* b3 = b2 + kstep;
;             if (last && has_next) S.a_ready(nxt);
;             if constexpr (SP2) {
;             PG8_LDB(B0, 0, 0); PG8_LDB(B1, 0, 1); PG8_SCHED; PG8_LDA(At, 0, 0); PG8_STAGE(PG8_SA(1, 1), a1 + hstep, voffA);
;             PG8_WAIT_V(8); PG8_WAIT_L(0); PG8_BAR; PG8_MMA(0, 0, At, B0); PG8_MMA(0, 1, At, B1); PG8_BAR; PG8_SCHED;
;             PG8_LDA(At, 0, 1); PG8_STAGE(PG8_SB(0, 0), b2, voffB); PG8_STAGE(PG8_SB(0, 1), b2 + hstep, voffB); PG8_STAGE(PG8_SA(0, 0), a2, voffA);
;             PG8_WAIT_V(8); PG8_WAIT_L(0); PG8_BAR; PG8_MMA(1, 0, At, B0); PG8_MMA(1, 1, At, B1); PG8_BAR; PG8_SCHED;
.LBB0_231:
	s_add_u32 s33, s42, 0xfff80080
	s_addc_u32 s44, s43, -1
	s_add_i32 s57, 0, 0x10000
	s_cmp_eq_u32 s29, 28
	s_cselect_b32 s47, s13, s44
	s_cselect_b32 s46, s25, s33
	s_cselect_b32 s45, s11, s28
	s_cselect_b32 s44, s26, s27
	s_add_i32 s33, 0, 0x14000
	v_add_u32_e32 v140, s57, v192
	v_add_u32_e32 v188, s33, v192
	ds_read_b128 v[128:131], v140
	ds_read_b128 v[132:135], v140 offset:1024
	ds_read_b128 v[136:139], v140 offset:2048
	ds_read_b128 v[140:143], v140 offset:3072
	ds_read_b128 v[176:179], v188
	ds_read_b128 v[180:183], v188 offset:1024
	ds_read_b128 v[184:187], v188 offset:2048
	ds_read_b128 v[198:201], v188 offset:3072
	v_lshl_add_u64 v[188:189], s[42:43], 0, v[172:173]
	s_add_i32 m0, s50, 0xc000
	ds_read_b128 v[202:205], v197
	ds_read_b128 v[206:209], v197 offset:1024
	ds_read_b128 v[210:213], v197 offset:2048
	ds_read_b128 v[220:223], v197 offset:3072
	ds_read_b128 v[224:227], v197 offset:4096
	ds_read_b128 v[228:231], v197 offset:5120
	ds_read_b128 v[232:235], v197 offset:6144
	ds_read_b128 v[236:239], v197 offset:7168
	global_load_lds_dwordx4 v[188:189], off
	v_lshl_add_u64 v[188:189], s[42:43], 0, v[174:175]
	s_add_i32 m0, s50, 0xe000
	s_nop 0
	global_load_lds_dwordx4 v[188:189], off
	s_waitcnt vmcnt(8)
	s_waitcnt lgkmcnt(0)
	s_setprio 1
	s_barrier
	v_mfma_f32_16x16x32_bf16 v[124:127], v[128:131], v[202:205], v[124:127]
	v_mfma_f32_16x16x32_bf16 v[120:123], v[136:139], v[202:205], v[120:123]
	v_mfma_f32_16x16x32_bf16 v[116:119], v[128:131], v[210:213], v[116:119]
	v_mfma_f32_16x16x32_bf16 v[112:115], v[136:139], v[210:213], v[112:115]
	v_mfma_f32_16x16x32_bf16 v[100:103], v[128:131], v[224:227], v[100:103]
	v_mfma_f32_16x16x32_bf16 v[96:99], v[136:139], v[224:227], v[96:99]
	v_mfma_f32_16x16x32_bf16 v[84:87], v[128:131], v[232:235], v[84:87]
	v_mfma_f32_16x16x32_bf16 v[80:83], v[136:139], v[232:235], v[80:83]
	v_mfma_f32_16x16x32_bf16 v[124:127], v[132:135], v[206:209], v[124:127]
	v_mfma_f32_16x16x32_bf16 v[120:123], v[140:143], v[206:209], v[120:123]
	v_mfma_f32_16x16x32_bf16 v[116:119], v[132:135], v[220:223], v[116:119]
	v_mfma_f32_16x16x32_bf16 v[112:115], v[140:143], v[220:223], v[112:115]
	v_mfma_f32_16x16x32_bf16 v[100:103], v[132:135], v[228:231], v[100:103]
	v_mfma_f32_16x16x32_bf16 v[96:99], v[140:143], v[228:231], v[96:99]
	v_mfma_f32_16x16x32_bf16 v[84:87], v[132:135], v[236:239], v[84:87]
	v_mfma_f32_16x16x32_bf16 v[80:83], v[140:143], v[236:239], v[80:83]
	v_mfma_f32_16x16x32_bf16 v[108:111], v[176:179], v[202:205], v[108:111]
	v_mfma_f32_16x16x32_bf16 v[104:107], v[184:187], v[202:205], v[104:107]
	v_mfma_f32_16x16x32_bf16 v[92:95], v[176:179], v[210:213], v[92:95]
	v_mfma_f32_16x16x32_bf16 v[88:91], v[184:187], v[210:213], v[88:91]
	v_mfma_f32_16x16x32_bf16 v[76:79], v[176:179], v[224:227], v[76:79]
	v_mfma_f32_16x16x32_bf16 v[72:75], v[184:187], v[224:227], v[72:75]
	v_mfma_f32_16x16x32_bf16 v[68:71], v[176:179], v[232:235], v[68:71]
	v_mfma_f32_16x16x32_bf16 v[64:67], v[184:187], v[232:235], v[64:67]
	v_mfma_f32_16x16x32_bf16 v[108:111], v[180:183], v[206:209], v[108:111]
	v_mfma_f32_16x16x32_bf16 v[104:107], v[198:201], v[206:209], v[104:107]
	v_mfma_f32_16x16x32_bf16 v[92:95], v[180:183], v[220:223], v[92:95]
	v_mfma_f32_16x16x32_bf16 v[88:91], v[198:201], v[220:223], v[88:91]
	v_mfma_f32_16x16x32_bf16 v[76:79], v[180:183], v[228:231], v[76:79]
	v_mfma_f32_16x16x32_bf16 v[72:75], v[198:201], v[228:231], v[72:75]
	v_mfma_f32_16x16x32_bf16 v[68:71], v[180:183], v[236:239], v[68:71]
	v_mfma_f32_16x16x32_bf16 v[64:67], v[198:201], v[236:239], v[64:67]
	s_barrier
	s_setprio 0
	s_add_i32 s57, s57, s48
	v_lshl_add_u64 v[188:189], s[44:45], 0, v[152:153]
	s_mov_b32 m0, s57
	ds_read_b128 v[202:205], v197 offset:16384
	ds_read_b128 v[206:209], v197 offset:17408
	ds_read_b128 v[210:213], v197 offset:18432
	ds_read_b128 v[220:223], v197 offset:19456
	ds_read_b128 v[224:227], v197 offset:20480
	ds_read_b128 v[228:231], v197 offset:21504
	ds_read_b128 v[232:235], v197 offset:22528
	ds_read_b128 v[236:239], v197 offset:23552
	global_load_lds_dwordx4 v[188:189], off
	s_add_i32 m0, s57, 0x2000
	s_add_u32 s58, s44, 0x80000
	v_lshl_add_u64 v[214:215], s[44:45], 0, v[144:145]
	s_addc_u32 s59, s45, 0
	s_add_i32 s33, s33, s48
	global_load_lds_dwordx4 v[214:215], off
	v_lshl_add_u64 v[240:241], s[58:59], 0, v[152:153]
	s_mov_b32 m0, s33
	v_lshl_add_u64 v[242:243], s[46:47], 0, v[146:147]
	global_load_lds_dwordx4 v[240:241], off
	v_lshl_add_u64 v[240:241], s[58:59], 0, v[144:145]
	s_add_i32 m0, s33, 0x2000
	s_nop 0
	global_load_lds_dwordx4 v[240:241], off
	v_lshl_add_u64 v[240:241], s[46:47], 0, v[148:149]
	s_mov_b32 m0, s50
	s_nop 0
	global_load_lds_dwordx4 v[240:241], off
	s_mov_b32 m0, s51
	s_nop 0
	global_load_lds_dwordx4 v[242:243], off
	s_waitcnt vmcnt(8)
	s_waitcnt lgkmcnt(0)
	s_setprio 1
	s_barrier
; #define PG8_STAGE(bufoff, gbase, voff) do { _Pragma("unroll") for (int _i = 0; _i < 2; ++_i) \
;         __builtin_amdgcn_global_load_lds((const unsigned*)((const char*)(gbase) + (voff)[_i]), (PG8_LAS unsigned*)(lds + (bufoff) + ldsw + _i * 8192), 16, 0, 0); } while (0)
; #define PG8_LDA(dst, b, h) do { _Pragma("unroll") for (int m = 0; m < 4; ++m) _Pragma("unroll") for (int k = 0; k < 2; ++k) dst[m][k] = *(const PG8_LAS bf16x8*)(lds + PG8_SA(b, h) + aoff + m * 2048 + k * 1024); } while (0)
; #define PG8_LDB(dst, b, h) do { _Pragma("unroll") for (int n = 0; n < 2; ++n) _Pragma("unroll") for (int k = 0; k < 2; ++k) dst[n][k] = *(const PG8_LAS bf16x8*)(lds + PG8_SB(b, h) + boff + n * 2048 + k * 1024); } while (0)
; #define PG8_MMA(ai, bj, At, Bt) do { __builtin_amdgcn_s_setprio(1); _Pragma("unroll") for (int m = 0; m < 4; ++m) _Pragma("unroll") for (int n = 0; n < 2; ++n) _Pragma("unroll") for (int k = 0; k < 2; ++k) \
;         acc[ai][bj][m][n] = __builtin_amdgcn_mfma_f32_16x16x32_bf16(Bt[n][k], At[m][k], acc[ai][bj][m][n], 0, 0, 0); __builtin_amdgcn_s_setprio(0); } while (0)
; #define PG8_WAIT_V(n) asm volatile("s_waitcnt vmcnt(" #n ")" ::: "memory")
; #define PG8_WAIT_L(n) asm volatile("s_waitcnt lgkmcnt(" #n ")" ::: "memory")
; #define PG8_BAR __builtin_amdgcn_s_barrier()
; #define PG8_SCHED __builtin_amdgcn_sched_barrier(0)
; template <class Epi, class Sched, bool ALIGN_EPI = false, bool SP2 = false>
; __device__ __forceinline__ void gemm_phase(PG8_LAS unsigned char* lds, const Gemm g, const Sched& S, const Epi& E) {
;     ...
;             PG8_WAIT_V(8); PG8_WAIT_L(0); PG8_BAR; PG8_MMA(1, 0, At, B0); PG8_MMA(1, 1, At, B1); PG8_BAR; PG8_SCHED;
;             PG8_LDB(B0, 1, 0); PG8_LDB(B1, 1, 1); PG8_SCHED; PG8_LDA(At, 1, 0); PG8_STAGE(PG8_SA(0, 1), a2 + hstep, voffA);
;             PG8_WAIT_V(8); PG8_WAIT_L(0); PG8_BAR; PG8_MMA(0, 0, At, B0); PG8_MMA(0, 1, At, B1); PG8_BAR; PG8_SCHED;
	v_mfma_f32_16x16x32_bf16 v[60:63], v[128:131], v[202:205], v[60:63]
	v_mfma_f32_16x16x32_bf16 v[56:59], v[136:139], v[202:205], v[56:59]
	v_mfma_f32_16x16x32_bf16 v[52:55], v[128:131], v[210:213], v[52:55]
	v_mfma_f32_16x16x32_bf16 v[48:51], v[136:139], v[210:213], v[48:51]
	v_mfma_f32_16x16x32_bf16 v[36:39], v[128:131], v[224:227], v[36:39]
	v_mfma_f32_16x16x32_bf16 v[32:35], v[136:139], v[224:227], v[32:35]
	v_mfma_f32_16x16x32_bf16 v[20:23], v[128:131], v[232:235], v[20:23]
	v_mfma_f32_16x16x32_bf16 v[16:19], v[136:139], v[232:235], v[16:19]
	v_mfma_f32_16x16x32_bf16 v[60:63], v[132:135], v[206:209], v[60:63]
	v_mfma_f32_16x16x32_bf16 v[56:59], v[140:143], v[206:209], v[56:59]
	v_mfma_f32_16x16x32_bf16 v[52:55], v[132:135], v[220:223], v[52:55]
	v_mfma_f32_16x16x32_bf16 v[48:51], v[140:143], v[220:223], v[48:51]
	v_mfma_f32_16x16x32_bf16 v[36:39], v[132:135], v[228:231], v[36:39]
	v_mfma_f32_16x16x32_bf16 v[32:35], v[140:143], v[228:231], v[32:35]
	v_mfma_f32_16x16x32_bf16 v[20:23], v[132:135], v[236:239], v[20:23]
	v_mfma_f32_16x16x32_bf16 v[16:19], v[140:143], v[236:239], v[16:19]
	v_mfma_f32_16x16x32_bf16 v[44:47], v[176:179], v[202:205], v[44:47]
	v_mfma_f32_16x16x32_bf16 v[40:43], v[184:187], v[202:205], v[40:43]
	v_mfma_f32_16x16x32_bf16 v[28:31], v[176:179], v[210:213], v[28:31]
	v_mfma_f32_16x16x32_bf16 v[24:27], v[184:187], v[210:213], v[24:27]
	v_mfma_f32_16x16x32_bf16 v[12:15], v[176:179], v[224:227], v[12:15]
	v_mfma_f32_16x16x32_bf16 v[8:11], v[184:187], v[224:227], v[8:11]
	v_mfma_f32_16x16x32_bf16 v[4:7], v[176:179], v[232:235], v[4:7]
	v_mfma_f32_16x16x32_bf16 v[0:3], v[184:187], v[232:235], v[0:3]
	v_mfma_f32_16x16x32_bf16 v[44:47], v[180:183], v[206:209], v[44:47]
	v_mfma_f32_16x16x32_bf16 v[40:43], v[198:201], v[206:209], v[40:43]
	v_mfma_f32_16x16x32_bf16 v[28:31], v[180:183], v[220:223], v[28:31]
	v_mfma_f32_16x16x32_bf16 v[24:27], v[198:201], v[220:223], v[24:27]
	v_mfma_f32_16x16x32_bf16 v[12:15], v[180:183], v[228:231], v[12:15]
	v_mfma_f32_16x16x32_bf16 v[8:11], v[198:201], v[228:231], v[8:11]
	v_mfma_f32_16x16x32_bf16 v[4:7], v[180:183], v[236:239], v[4:7]
	v_mfma_f32_16x16x32_bf16 v[0:3], v[198:201], v[236:239], v[0:3]
	s_barrier
	s_setprio 0
	s_add_i32 s33, 0, 0x18000
	s_add_i32 s57, 0, 0x1c000
	v_add_u32_e32 v140, s33, v192
	v_add_u32_e32 v198, s57, v192
	ds_read_b128 v[128:131], v140
	ds_read_b128 v[132:135], v140 offset:1024
	ds_read_b128 v[136:139], v140 offset:2048
	ds_read_b128 v[140:143], v140 offset:3072
	ds_read_b128 v[176:179], v198
	ds_read_b128 v[180:183], v198 offset:1024
	ds_read_b128 v[184:187], v198 offset:2048
	ds_read_b128 v[198:201], v198 offset:3072
	s_add_u32 s46, s46, 0x80000
	s_addc_u32 s47, s47, 0
	s_mov_b32 m0, s52
	v_lshl_add_u64 v[244:245], s[46:47], 0, v[148:149]
	ds_read_b128 v[202:205], v197 offset:32768
	ds_read_b128 v[206:209], v197 offset:33792
	ds_read_b128 v[210:213], v197 offset:34816
	ds_read_b128 v[220:223], v197 offset:35840
	ds_read_b128 v[224:227], v197 offset:36864
	ds_read_b128 v[228:231], v197 offset:37888
	ds_read_b128 v[232:235], v197 offset:38912
	ds_read_b128 v[236:239], v197 offset:39936
	global_load_lds_dwordx4 v[244:245], off
	v_lshl_add_u64 v[244:245], s[46:47], 0, v[146:147]
	s_mov_b32 m0, s53
	s_nop 0
	global_load_lds_dwordx4 v[244:245], off
	s_waitcnt vmcnt(8)
	s_waitcnt lgkmcnt(0)
	s_setprio 1
	s_barrier
	v_mfma_f32_16x16x32_bf16 v[124:127], v[128:131], v[202:205], v[124:127]
	v_mfma_f32_16x16x32_bf16 v[120:123], v[136:139], v[202:205], v[120:123]
	v_mfma_f32_16x16x32_bf16 v[116:119], v[128:131], v[210:213], v[116:119]
	v_mfma_f32_16x16x32_bf16 v[112:115], v[136:139], v[210:213], v[112:115]
	v_mfma_f32_16x16x32_bf16 v[100:103], v[128:131], v[224:227], v[100:103]
	v_mfma_f32_16x16x32_bf16 v[96:99], v[136:139], v[224:227], v[96:99]
	v_mfma_f32_16x16x32_bf16 v[84:87], v[128:131], v[232:235], v[84:87]
	v_mfma_f32_16x16x32_bf16 v[80:83], v[136:139], v[232:235], v[80:83]
	v_mfma_f32_16x16x32_bf16 v[124:127], v[132:135], v[206:209], v[124:127]
	v_mfma_f32_16x16x32_bf16 v[120:123], v[140:143], v[206:209], v[120:123]
	v_mfma_f32_16x16x32_bf16 v[116:119], v[132:135], v[220:223], v[116:119]
	v_mfma_f32_16x16x32_bf16 v[112:115], v[140:143], v[220:223], v[112:115]
	v_mfma_f32_16x16x32_bf16 v[100:103], v[132:135], v[228:231], v[100:103]
	v_mfma_f32_16x16x32_bf16 v[96:99], v[140:143], v[228:231], v[96:99]
	v_mfma_f32_16x16x32_bf16 v[84:87], v[132:135], v[236:239], v[84:87]
	v_mfma_f32_16x16x32_bf16 v[80:83], v[140:143], v[236:239], v[80:83]
	v_mfma_f32_16x16x32_bf16 v[108:111], v[176:179], v[202:205], v[108:111]
	v_mfma_f32_16x16x32_bf16 v[104:107], v[184:187], v[202:205], v[104:107]
	v_mfma_f32_16x16x32_bf16 v[92:95], v[176:179], v[210:213], v[92:95]
	v_mfma_f32_16x16x32_bf16 v[88:91], v[184:187], v[210:213], v[88:91]
	v_mfma_f32_16x16x32_bf16 v[76:79], v[176:179], v[224:227], v[76:79]
	v_mfma_f32_16x16x32_bf16 v[72:75], v[184:187], v[224:227], v[72:75]
	v_mfma_f32_16x16x32_bf16 v[68:71], v[176:179], v[232:235], v[68:71]
	v_mfma_f32_16x16x32_bf16 v[64:67], v[184:187], v[232:235], v[64:67]
	v_mfma_f32_16x16x32_bf16 v[108:111], v[180:183], v[206:209], v[108:111]
	v_mfma_f32_16x16x32_bf16 v[104:107], v[198:201], v[206:209], v[104:107]
	v_mfma_f32_16x16x32_bf16 v[92:95], v[180:183], v[220:223], v[92:95]
	v_mfma_f32_16x16x32_bf16 v[88:91], v[198:201], v[220:223], v[88:91]
	v_mfma_f32_16x16x32_bf16 v[76:79], v[180:183], v[228:231], v[76:79]
	v_mfma_f32_16x16x32_bf16 v[72:75], v[198:201], v[228:231], v[72:75]
	v_mfma_f32_16x16x32_bf16 v[68:71], v[180:183], v[236:239], v[68:71]
	v_mfma_f32_16x16x32_bf16 v[64:67], v[198:201], v[236:239], v[64:67]
	s_barrier
; #define PG8_STAGE(bufoff, gbase, voff) do { _Pragma("unroll") for (int _i = 0; _i < 2; ++_i) \
;         __builtin_amdgcn_global_load_lds((const unsigned*)((const char*)(gbase) + (voff)[_i]), (PG8_LAS unsigned*)(lds + (bufoff) + ldsw + _i * 8192), 16, 0, 0); } while (0)
; #define PG8_LDA(dst, b, h) do { _Pragma("unroll") for (int m = 0; m < 4; ++m) _Pragma("unroll") for (int k = 0; k < 2; ++k) dst[m][k] = *(const PG8_LAS bf16x8*)(lds + PG8_SA(b, h) + aoff + m * 2048 + k * 1024); } while (0)
; #define PG8_MMA(ai, bj, At, Bt) do { __builtin_amdgcn_s_setprio(1); _Pragma("unroll") for (int m = 0; m < 4; ++m) _Pragma("unroll") for (int n = 0; n < 2; ++n) _Pragma("unroll") for (int k = 0; k < 2; ++k) \
;         acc[ai][bj][m][n] = __builtin_amdgcn_mfma_f32_16x16x32_bf16(Bt[n][k], At[m][k], acc[ai][bj][m][n], 0, 0, 0); __builtin_amdgcn_s_setprio(0); } while (0)
; #define PG8_WAIT_V(n) asm volatile("s_waitcnt vmcnt(" #n ")" ::: "memory")
; #define PG8_WAIT_L(n) asm volatile("s_waitcnt lgkmcnt(" #n ")" ::: "memory")
; #define PG8_BAR __builtin_amdgcn_s_barrier()
; #define PG8_SCHED __builtin_amdgcn_sched_barrier(0)
; template <class Epi, class Sched, bool ALIGN_EPI = false, bool SP2 = false>
; __device__ __forceinline__ void gemm_phase(PG8_LAS unsigned char* lds, const Gemm g, const Sched& S, const Epi& E) {
;     ...
;         for (int t = 0; t < nt; t += 2) {
;             const bool last = (t == nt - 2);
;             const char* a1 = cA + (size_t)(t + 1) * kstep;
;             const char* a2 = last ? nA : cA + (size_t)(t + 2) * kstep; const char* b2 = last ? nB : cB + (size_t)(t + 2) * kstep;
;     ...
;             PG8_LDA(At, 1, 1); PG8_STAGE(PG8_SB(1, 0), b3, voffB); PG8_STAGE(PG8_SB(1, 1), b3 + hstep, voffB); PG8_STAGE(PG8_SA(1, 0), a3, voffA);
;             PG8_WAIT_V(8); PG8_WAIT_L(0); PG8_BAR; PG8_MMA(1, 0, At, B0); PG8_MMA(1, 1, At, B1); PG8_BAR; PG8_SCHED;
	s_setprio 0
	s_add_i32 s33, s33, s48
	v_lshl_add_u64 v[188:189], v[188:189], 0, s[90:91]
	s_mov_b32 m0, s33
	ds_read_b128 v[202:205], v197 offset:49152
	ds_read_b128 v[206:209], v197 offset:50176
	ds_read_b128 v[210:213], v197 offset:51200
	ds_read_b128 v[220:223], v197 offset:52224
	ds_read_b128 v[224:227], v197 offset:53248
	ds_read_b128 v[228:231], v197 offset:54272
	ds_read_b128 v[232:235], v197 offset:55296
	ds_read_b128 v[236:239], v197 offset:56320
	global_load_lds_dwordx4 v[188:189], off
	s_add_i32 m0, s33, 0x2000
	s_add_u32 s44, s44, 0x80080
	v_lshl_add_u64 v[188:189], v[214:215], 0, s[90:91]
	s_addc_u32 s45, s45, 0
	s_add_i32 s33, s57, s48
	global_load_lds_dwordx4 v[188:189], off
	v_lshl_add_u64 v[188:189], s[44:45], 0, v[152:153]
	s_mov_b32 m0, s33
	s_nop 0
	global_load_lds_dwordx4 v[188:189], off
	v_lshl_add_u64 v[188:189], s[44:45], 0, v[144:145]
	s_add_i32 m0, s33, 0x2000
	s_nop 0
	global_load_lds_dwordx4 v[188:189], off
	v_lshl_add_u64 v[188:189], v[240:241], 0, s[90:91]
	s_mov_b32 m0, s4
	s_nop 0
	global_load_lds_dwordx4 v[188:189], off
	v_lshl_add_u64 v[188:189], v[242:243], 0, s[90:91]
	s_mov_b32 m0, s54
	s_nop 0
	global_load_lds_dwordx4 v[188:189], off
	s_waitcnt vmcnt(8)
	s_waitcnt lgkmcnt(0)
	s_setprio 1
	s_barrier
	v_mfma_f32_16x16x32_bf16 v[60:63], v[128:131], v[202:205], v[60:63]
	v_mfma_f32_16x16x32_bf16 v[56:59], v[136:139], v[202:205], v[56:59]
	v_mfma_f32_16x16x32_bf16 v[52:55], v[128:131], v[210:213], v[52:55]
	v_mfma_f32_16x16x32_bf16 v[48:51], v[136:139], v[210:213], v[48:51]
	v_mfma_f32_16x16x32_bf16 v[36:39], v[128:131], v[224:227], v[36:39]
	v_mfma_f32_16x16x32_bf16 v[32:35], v[136:139], v[224:227], v[32:35]
	v_mfma_f32_16x16x32_bf16 v[20:23], v[128:131], v[232:235], v[20:23]
	v_mfma_f32_16x16x32_bf16 v[16:19], v[136:139], v[232:235], v[16:19]
	v_mfma_f32_16x16x32_bf16 v[60:63], v[132:135], v[206:209], v[60:63]
	v_mfma_f32_16x16x32_bf16 v[56:59], v[140:143], v[206:209], v[56:59]
	v_mfma_f32_16x16x32_bf16 v[52:55], v[132:135], v[220:223], v[52:55]
	v_mfma_f32_16x16x32_bf16 v[48:51], v[140:143], v[220:223], v[48:51]
	v_mfma_f32_16x16x32_bf16 v[36:39], v[132:135], v[228:231], v[36:39]
	v_mfma_f32_16x16x32_bf16 v[32:35], v[140:143], v[228:231], v[32:35]
	v_mfma_f32_16x16x32_bf16 v[20:23], v[132:135], v[236:239], v[20:23]
	v_mfma_f32_16x16x32_bf16 v[16:19], v[140:143], v[236:239], v[16:19]
	v_mfma_f32_16x16x32_bf16 v[44:47], v[176:179], v[202:205], v[44:47]
	v_mfma_f32_16x16x32_bf16 v[40:43], v[184:187], v[202:205], v[40:43]
	v_mfma_f32_16x16x32_bf16 v[28:31], v[176:179], v[210:213], v[28:31]
	v_mfma_f32_16x16x32_bf16 v[24:27], v[184:187], v[210:213], v[24:27]
	v_mfma_f32_16x16x32_bf16 v[12:15], v[176:179], v[224:227], v[12:15]
	v_mfma_f32_16x16x32_bf16 v[8:11], v[184:187], v[224:227], v[8:11]
	v_mfma_f32_16x16x32_bf16 v[4:7], v[176:179], v[232:235], v[4:7]
	v_mfma_f32_16x16x32_bf16 v[0:3], v[184:187], v[232:235], v[0:3]
	v_mfma_f32_16x16x32_bf16 v[44:47], v[180:183], v[206:209], v[44:47]
	v_mfma_f32_16x16x32_bf16 v[40:43], v[198:201], v[206:209], v[40:43]
	v_mfma_f32_16x16x32_bf16 v[28:31], v[180:183], v[220:223], v[28:31]
	v_mfma_f32_16x16x32_bf16 v[24:27], v[198:201], v[220:223], v[24:27]
	v_mfma_f32_16x16x32_bf16 v[12:15], v[180:183], v[228:231], v[12:15]
	v_mfma_f32_16x16x32_bf16 v[8:11], v[198:201], v[228:231], v[8:11]
	v_mfma_f32_16x16x32_bf16 v[4:7], v[180:183], v[236:239], v[4:7]
	v_mfma_f32_16x16x32_bf16 v[0:3], v[198:201], v[236:239], v[0:3]
	s_barrier
	s_setprio 0
	s_add_i32 s29, s29, 2
	s_add_u32 s42, s42, 0x100
	s_addc_u32 s43, s43, 0
	s_add_u32 s27, s27, 0x100
	s_addc_u32 s28, s28, 0
	s_cmp_gt_u32 s29, 29
	s_cbranch_scc0 .LBB0_231
	s_and_b64 vcc, exec, s[8:9]
	s_cbranch_vccz .LBB0_234
	s_barrier

; #define PG8_STAGE(bufoff, gbase, voff) do { _Pragma("unroll") for (int _i = 0; _i < 2; ++_i) \
;         __builtin_amdgcn_global_load_lds((const unsigned*)((const char*)(gbase) + (voff)[_i]), (PG8_LAS unsigned*)(lds + (bufoff) + ldsw + _i * 8192), 16, 0, 0); } while (0)
; #define PG8_LDA(dst, b, h) do { _Pragma("unroll") for (int m = 0; m < 4; ++m) _Pragma("unroll") for (int k = 0; k < 2; ++k) dst[m][k] = *(const PG8_LAS bf16x8*)(lds + PG8_SA(b, h) + aoff + m * 2048 + k * 1024); } while (0)
; #define PG8_LDB(dst, b, h) do { _Pragma("unroll") for (int n = 0; n < 2; ++n) _Pragma("unroll") for (int k = 0; k < 2; ++k) dst[n][k] = *(const PG8_LAS bf16x8*)(lds + PG8_SB(b, h) + boff + n * 2048 + k * 1024); } while (0)
; #define PG8_MMA(ai, bj, At, Bt) do { __builtin_amdgcn_s_setprio(1); _Pragma("unroll") for (int m = 0; m < 4; ++m) _Pragma("unroll") for (int n = 0; n < 2; ++n) _Pragma("unroll") for (int k = 0; k < 2; ++k) \
;         acc[ai][bj][m][n] = __builtin_amdgcn_mfma_f32_16x16x32_bf16(Bt[n][k], At[m][k], acc[ai][bj][m][n], 0, 0, 0); __builtin_amdgcn_s_setprio(0); } while (0)
; #define PG8_BAR __builtin_amdgcn_s_barrier()
; template <class Epi, class Sched, bool ALIGN_EPI = false, bool SP2 = false>
; __device__ __forceinline__ void gemm_phase(PG8_LAS unsigned char* lds, const Gemm g, const Sched& S, const Epi& E) {
;     ...
;         const bool has_next = S.next(ui + 1, nxt);
;         const char* nA = has_next ? (const char*)g.A + (size_t)nxt.pm * tstep : cA; const char* nB = has_next ? (const char*)g.Bt + (size_t)nxt.pn * tstep : cB;
;         for (int t = 0; t < nt; t += 2) {
;             const bool last = (t == nt - 2);
;             const char* a1 = cA + (size_t)(t + 1) * kstep;
;             const char* a2 = last ? nA : cA + (size_t)(t + 2) * kstep; const char* b2 = last ? nB : cB + (size_t)(t + 2) * kstep;
;             const char* a3 = a2 + kstep; const char* b3 = b2 + kstep;
;             if (last && has_next) S.a_ready(nxt);
;             if constexpr (SP2) {
;             PG8_LDB(B0, 0, 0); PG8_LDB(B1, 0, 1); PG8_SCHED; PG8_LDA(At, 0, 0); PG8_STAGE(PG8_SA(1, 1), a1 + hstep, voffA);
;             PG8_WAIT_V(8); PG8_WAIT_L(0); PG8_BAR; PG8_MMA(0, 0, At, B0); PG8_MMA(0, 1, At, B1); PG8_BAR; PG8_SCHED;
;             PG8_LDA(At, 0, 1); PG8_STAGE(PG8_SB(0, 0), b2, voffB); PG8_STAGE(PG8_SB(0, 1), b2 + hstep, voffB); PG8_STAGE(PG8_SA(0, 0), a2, voffA);
.LBB0_291:
	s_add_u32 s18, s16, 0x14aba100
	s_addc_u32 s19, s17, 0
	s_add_u32 s44, s16, s41
	s_addc_u32 s45, s17, s42
	s_cmp_eq_u32 s43, 28
	s_cselect_b32 s39, s89, s19
	s_cselect_b32 s38, s88, s18
	s_cselect_b32 s19, s15, s45
	s_cselect_b32 s18, s14, s44
	s_add_i32 s44, 0, 0x10000
	v_add_u32_e32 v150, s44, v140
	s_add_i32 s46, 0, 0x14000
	ds_read_b128 v[142:145], v150
	ds_read_b128 v[146:149], v150 offset:1024
	ds_read_b128 v[170:173], v150 offset:2048
	ds_read_b128 v[174:177], v150 offset:3072
	v_add_u32_e32 v150, s46, v140
	ds_read_b128 v[178:181], v150
	ds_read_b128 v[182:185], v150 offset:1024
	ds_read_b128 v[186:189], v150 offset:2048
	ds_read_b128 v[190:193], v150 offset:3072
	v_lshl_add_u64 v[150:151], s[16:17], 0, v[134:135]
	s_add_i32 m0, s13, 0xc000
	ds_read_b128 v[194:197], v141
	ds_read_b128 v[198:201], v141 offset:1024
	ds_read_b128 v[202:205], v141 offset:2048
	ds_read_b128 v[206:209], v141 offset:3072
	ds_read_b128 v[210:213], v141 offset:4096
	ds_read_b128 v[220:223], v141 offset:5120
	ds_read_b128 v[224:227], v141 offset:6144
	ds_read_b128 v[228:231], v141 offset:7168
	global_load_lds_dwordx4 v[150:151], off
	v_lshl_add_u64 v[150:151], s[16:17], 0, v[136:137]
	s_add_i32 m0, s13, 0xe000
	s_nop 0
	global_load_lds_dwordx4 v[150:151], off
	s_waitcnt vmcnt(8)
	s_waitcnt lgkmcnt(0)
	s_setprio 1
	s_barrier
	v_mfma_f32_16x16x32_bf16 v[124:127], v[142:145], v[194:197], v[124:127]
	v_mfma_f32_16x16x32_bf16 v[120:123], v[170:173], v[194:197], v[120:123]
	v_mfma_f32_16x16x32_bf16 v[108:111], v[142:145], v[202:205], v[108:111]
	v_mfma_f32_16x16x32_bf16 v[104:107], v[170:173], v[202:205], v[104:107]
	v_mfma_f32_16x16x32_bf16 v[92:95], v[142:145], v[210:213], v[92:95]
	v_mfma_f32_16x16x32_bf16 v[88:91], v[170:173], v[210:213], v[88:91]
	v_mfma_f32_16x16x32_bf16 v[76:79], v[142:145], v[224:227], v[76:79]
	v_mfma_f32_16x16x32_bf16 v[72:75], v[170:173], v[224:227], v[72:75]
	v_mfma_f32_16x16x32_bf16 v[124:127], v[146:149], v[198:201], v[124:127]
	v_mfma_f32_16x16x32_bf16 v[120:123], v[174:177], v[198:201], v[120:123]
	v_mfma_f32_16x16x32_bf16 v[108:111], v[146:149], v[206:209], v[108:111]
	v_mfma_f32_16x16x32_bf16 v[104:107], v[174:177], v[206:209], v[104:107]
	v_mfma_f32_16x16x32_bf16 v[92:95], v[146:149], v[220:223], v[92:95]
	v_mfma_f32_16x16x32_bf16 v[88:91], v[174:177], v[220:223], v[88:91]
	v_mfma_f32_16x16x32_bf16 v[76:79], v[146:149], v[228:231], v[76:79]
	v_mfma_f32_16x16x32_bf16 v[72:75], v[174:177], v[228:231], v[72:75]
	v_mfma_f32_16x16x32_bf16 v[116:119], v[178:181], v[194:197], v[116:119]
	v_mfma_f32_16x16x32_bf16 v[112:115], v[186:189], v[194:197], v[112:115]
	v_mfma_f32_16x16x32_bf16 v[100:103], v[178:181], v[202:205], v[100:103]
	v_mfma_f32_16x16x32_bf16 v[96:99], v[186:189], v[202:205], v[96:99]
	v_mfma_f32_16x16x32_bf16 v[84:87], v[178:181], v[210:213], v[84:87]
	v_mfma_f32_16x16x32_bf16 v[80:83], v[186:189], v[210:213], v[80:83]
	v_mfma_f32_16x16x32_bf16 v[68:71], v[178:181], v[224:227], v[68:71]
	v_mfma_f32_16x16x32_bf16 v[64:67], v[186:189], v[224:227], v[64:67]
	v_mfma_f32_16x16x32_bf16 v[116:119], v[182:185], v[198:201], v[116:119]
	v_mfma_f32_16x16x32_bf16 v[112:115], v[190:193], v[198:201], v[112:115]
	v_mfma_f32_16x16x32_bf16 v[100:103], v[182:185], v[206:209], v[100:103]
	v_mfma_f32_16x16x32_bf16 v[96:99], v[190:193], v[206:209], v[96:99]
	v_mfma_f32_16x16x32_bf16 v[84:87], v[182:185], v[220:223], v[84:87]
	v_mfma_f32_16x16x32_bf16 v[80:83], v[190:193], v[220:223], v[80:83]
	v_mfma_f32_16x16x32_bf16 v[68:71], v[182:185], v[228:231], v[68:71]
	v_mfma_f32_16x16x32_bf16 v[64:67], v[190:193], v[228:231], v[64:67]
	s_barrier
	s_setprio 0
	s_add_i32 s44, s44, s26
	v_lshl_add_u64 v[150:151], s[18:19], 0, v[152:153]
	s_mov_b32 m0, s44
	ds_read_b128 v[194:197], v141 offset:16384
	ds_read_b128 v[198:201], v141 offset:17408
	ds_read_b128 v[202:205], v141 offset:18432
	ds_read_b128 v[206:209], v141 offset:19456
	ds_read_b128 v[210:213], v141 offset:20480
	ds_read_b128 v[220:223], v141 offset:21504
	ds_read_b128 v[224:227], v141 offset:22528
	ds_read_b128 v[228:231], v141 offset:23552
	global_load_lds_dwordx4 v[150:151], off
	s_add_i32 m0, s44, 0x2000
	s_add_u32 s44, s18, 0x80000
	v_lshl_add_u64 v[214:215], s[18:19], 0, v[128:129]
	s_addc_u32 s45, s19, 0
	s_add_i32 s46, s46, s26
	global_load_lds_dwordx4 v[214:215], off
	v_lshl_add_u64 v[232:233], s[44:45], 0, v[152:153]
	s_mov_b32 m0, s46
	v_lshl_add_u64 v[234:235], s[38:39], 0, v[130:131]
	global_load_lds_dwordx4 v[232:233], off
	v_lshl_add_u64 v[232:233], s[44:45], 0, v[128:129]
	s_add_i32 m0, s46, 0x2000
	s_nop 0
	global_load_lds_dwordx4 v[232:233], off
	v_lshl_add_u64 v[232:233], s[38:39], 0, v[132:133]
	s_mov_b32 m0, s13
	s_nop 0
	global_load_lds_dwordx4 v[232:233], off
	s_mov_b32 m0, s27
	s_nop 0
	global_load_lds_dwordx4 v[234:235], off
	s_waitcnt vmcnt(8)
	s_waitcnt lgkmcnt(0)
	s_setprio 1
	s_barrier
; #define PG8_STAGE(bufoff, gbase, voff) do { _Pragma("unroll") for (int _i = 0; _i < 2; ++_i) \
;         __builtin_amdgcn_global_load_lds((const unsigned*)((const char*)(gbase) + (voff)[_i]), (PG8_LAS unsigned*)(lds + (bufoff) + ldsw + _i * 8192), 16, 0, 0); } while (0)
; #define PG8_LDA(dst, b, h) do { _Pragma("unroll") for (int m = 0; m < 4; ++m) _Pragma("unroll") for (int k = 0; k < 2; ++k) dst[m][k] = *(const PG8_LAS bf16x8*)(lds + PG8_SA(b, h) + aoff + m * 2048 + k * 1024); } while (0)
; #define PG8_LDB(dst, b, h) do { _Pragma("unroll") for (int n = 0; n < 2; ++n) _Pragma("unroll") for (int k = 0; k < 2; ++k) dst[n][k] = *(const PG8_LAS bf16x8*)(lds + PG8_SB(b, h) + boff + n * 2048 + k * 1024); } while (0)
; #define PG8_MMA(ai, bj, At, Bt) do { __builtin_amdgcn_s_setprio(1); _Pragma("unroll") for (int m = 0; m < 4; ++m) _Pragma("unroll") for (int n = 0; n < 2; ++n) _Pragma("unroll") for (int k = 0; k < 2; ++k) \
;         acc[ai][bj][m][n] = __builtin_amdgcn_mfma_f32_16x16x32_bf16(Bt[n][k], At[m][k], acc[ai][bj][m][n], 0, 0, 0); __builtin_amdgcn_s_setprio(0); } while (0)
; #define PG8_WAIT_V(n) asm volatile("s_waitcnt vmcnt(" #n ")" ::: "memory")
; #define PG8_WAIT_L(n) asm volatile("s_waitcnt lgkmcnt(" #n ")" ::: "memory")
; #define PG8_BAR __builtin_amdgcn_s_barrier()
; #define PG8_SCHED __builtin_amdgcn_sched_barrier(0)
; template <class Epi, class Sched, bool ALIGN_EPI = false, bool SP2 = false>
; __device__ __forceinline__ void gemm_phase(PG8_LAS unsigned char* lds, const Gemm g, const Sched& S, const Epi& E) {
;     ...
;             PG8_WAIT_V(8); PG8_WAIT_L(0); PG8_BAR; PG8_MMA(1, 0, At, B0); PG8_MMA(1, 1, At, B1); PG8_BAR; PG8_SCHED;
;             PG8_LDB(B0, 1, 0); PG8_LDB(B1, 1, 1); PG8_SCHED; PG8_LDA(At, 1, 0); PG8_STAGE(PG8_SA(0, 1), a2 + hstep, voffA);
;             PG8_WAIT_V(8); PG8_WAIT_L(0); PG8_BAR; PG8_MMA(0, 0, At, B0); PG8_MMA(0, 1, At, B1); PG8_BAR; PG8_SCHED;
	v_mfma_f32_16x16x32_bf16 v[60:63], v[142:145], v[194:197], v[60:63]
	v_mfma_f32_16x16x32_bf16 v[56:59], v[170:173], v[194:197], v[56:59]
	v_mfma_f32_16x16x32_bf16 v[44:47], v[142:145], v[202:205], v[44:47]
	v_mfma_f32_16x16x32_bf16 v[40:43], v[170:173], v[202:205], v[40:43]
	v_mfma_f32_16x16x32_bf16 v[28:31], v[142:145], v[210:213], v[28:31]
	v_mfma_f32_16x16x32_bf16 v[24:27], v[170:173], v[210:213], v[24:27]
	v_mfma_f32_16x16x32_bf16 v[12:15], v[142:145], v[224:227], v[12:15]
	v_mfma_f32_16x16x32_bf16 v[8:11], v[170:173], v[224:227], v[8:11]
	v_mfma_f32_16x16x32_bf16 v[60:63], v[146:149], v[198:201], v[60:63]
	v_mfma_f32_16x16x32_bf16 v[56:59], v[174:177], v[198:201], v[56:59]
	v_mfma_f32_16x16x32_bf16 v[44:47], v[146:149], v[206:209], v[44:47]
	v_mfma_f32_16x16x32_bf16 v[40:43], v[174:177], v[206:209], v[40:43]
	v_mfma_f32_16x16x32_bf16 v[28:31], v[146:149], v[220:223], v[28:31]
	v_mfma_f32_16x16x32_bf16 v[24:27], v[174:177], v[220:223], v[24:27]
	v_mfma_f32_16x16x32_bf16 v[12:15], v[146:149], v[228:231], v[12:15]
	v_mfma_f32_16x16x32_bf16 v[8:11], v[174:177], v[228:231], v[8:11]
	v_mfma_f32_16x16x32_bf16 v[52:55], v[178:181], v[194:197], v[52:55]
	v_mfma_f32_16x16x32_bf16 v[48:51], v[186:189], v[194:197], v[48:51]
	v_mfma_f32_16x16x32_bf16 v[36:39], v[178:181], v[202:205], v[36:39]
	v_mfma_f32_16x16x32_bf16 v[32:35], v[186:189], v[202:205], v[32:35]
	v_mfma_f32_16x16x32_bf16 v[20:23], v[178:181], v[210:213], v[20:23]
	v_mfma_f32_16x16x32_bf16 v[16:19], v[186:189], v[210:213], v[16:19]
	v_mfma_f32_16x16x32_bf16 v[4:7], v[178:181], v[224:227], v[4:7]
	v_mfma_f32_16x16x32_bf16 v[0:3], v[186:189], v[224:227], v[0:3]
	v_mfma_f32_16x16x32_bf16 v[52:55], v[182:185], v[198:201], v[52:55]
	v_mfma_f32_16x16x32_bf16 v[48:51], v[190:193], v[198:201], v[48:51]
	v_mfma_f32_16x16x32_bf16 v[36:39], v[182:185], v[206:209], v[36:39]
	v_mfma_f32_16x16x32_bf16 v[32:35], v[190:193], v[206:209], v[32:35]
	v_mfma_f32_16x16x32_bf16 v[20:23], v[182:185], v[220:223], v[20:23]
	v_mfma_f32_16x16x32_bf16 v[16:19], v[190:193], v[220:223], v[16:19]
	v_mfma_f32_16x16x32_bf16 v[4:7], v[182:185], v[228:231], v[4:7]
	v_mfma_f32_16x16x32_bf16 v[0:3], v[190:193], v[228:231], v[0:3]
	s_barrier
	s_setprio 0
	s_add_i32 s44, 0, 0x18000
	s_add_i32 s45, 0, 0x1c000
	v_add_u32_e32 v174, s44, v140
	v_add_u32_e32 v190, s45, v140
	ds_read_b128 v[142:145], v174
	ds_read_b128 v[146:149], v174 offset:1024
	ds_read_b128 v[170:173], v174 offset:2048
	ds_read_b128 v[174:177], v174 offset:3072
	ds_read_b128 v[178:181], v190
	ds_read_b128 v[182:185], v190 offset:1024
	ds_read_b128 v[186:189], v190 offset:2048
	ds_read_b128 v[190:193], v190 offset:3072
	s_add_u32 s38, s38, 0x80000
	s_addc_u32 s39, s39, 0
	s_mov_b32 m0, s28
	v_lshl_add_u64 v[236:237], s[38:39], 0, v[132:133]
	ds_read_b128 v[194:197], v141 offset:32768
	ds_read_b128 v[198:201], v141 offset:33792
	ds_read_b128 v[202:205], v141 offset:34816
	ds_read_b128 v[206:209], v141 offset:35840
	ds_read_b128 v[210:213], v141 offset:36864
	ds_read_b128 v[220:223], v141 offset:37888
	ds_read_b128 v[224:227], v141 offset:38912
	ds_read_b128 v[228:231], v141 offset:39936
	global_load_lds_dwordx4 v[236:237], off
	v_lshl_add_u64 v[236:237], s[38:39], 0, v[130:131]
	s_mov_b32 m0, s29
	s_nop 0
	global_load_lds_dwordx4 v[236:237], off
	s_waitcnt vmcnt(8)
	s_waitcnt lgkmcnt(0)
	s_setprio 1
	s_barrier
	v_mfma_f32_16x16x32_bf16 v[124:127], v[142:145], v[194:197], v[124:127]
	v_mfma_f32_16x16x32_bf16 v[120:123], v[170:173], v[194:197], v[120:123]
	v_mfma_f32_16x16x32_bf16 v[108:111], v[142:145], v[202:205], v[108:111]
	v_mfma_f32_16x16x32_bf16 v[104:107], v[170:173], v[202:205], v[104:107]
	v_mfma_f32_16x16x32_bf16 v[92:95], v[142:145], v[210:213], v[92:95]
	v_mfma_f32_16x16x32_bf16 v[88:91], v[170:173], v[210:213], v[88:91]
	v_mfma_f32_16x16x32_bf16 v[76:79], v[142:145], v[224:227], v[76:79]
	v_mfma_f32_16x16x32_bf16 v[72:75], v[170:173], v[224:227], v[72:75]
	v_mfma_f32_16x16x32_bf16 v[124:127], v[146:149], v[198:201], v[124:127]
	v_mfma_f32_16x16x32_bf16 v[120:123], v[174:177], v[198:201], v[120:123]
	v_mfma_f32_16x16x32_bf16 v[108:111], v[146:149], v[206:209], v[108:111]
	v_mfma_f32_16x16x32_bf16 v[104:107], v[174:177], v[206:209], v[104:107]
	v_mfma_f32_16x16x32_bf16 v[92:95], v[146:149], v[220:223], v[92:95]
	v_mfma_f32_16x16x32_bf16 v[88:91], v[174:177], v[220:223], v[88:91]
	v_mfma_f32_16x16x32_bf16 v[76:79], v[146:149], v[228:231], v[76:79]
	v_mfma_f32_16x16x32_bf16 v[72:75], v[174:177], v[228:231], v[72:75]
	v_mfma_f32_16x16x32_bf16 v[116:119], v[178:181], v[194:197], v[116:119]
	v_mfma_f32_16x16x32_bf16 v[112:115], v[186:189], v[194:197], v[112:115]
	v_mfma_f32_16x16x32_bf16 v[100:103], v[178:181], v[202:205], v[100:103]
	v_mfma_f32_16x16x32_bf16 v[96:99], v[186:189], v[202:205], v[96:99]
	v_mfma_f32_16x16x32_bf16 v[84:87], v[178:181], v[210:213], v[84:87]
	v_mfma_f32_16x16x32_bf16 v[80:83], v[186:189], v[210:213], v[80:83]
	v_mfma_f32_16x16x32_bf16 v[68:71], v[178:181], v[224:227], v[68:71]
	v_mfma_f32_16x16x32_bf16 v[64:67], v[186:189], v[224:227], v[64:67]
	v_mfma_f32_16x16x32_bf16 v[116:119], v[182:185], v[198:201], v[116:119]
	v_mfma_f32_16x16x32_bf16 v[112:115], v[190:193], v[198:201], v[112:115]
	v_mfma_f32_16x16x32_bf16 v[100:103], v[182:185], v[206:209], v[100:103]
	v_mfma_f32_16x16x32_bf16 v[96:99], v[190:193], v[206:209], v[96:99]
	v_mfma_f32_16x16x32_bf16 v[84:87], v[182:185], v[220:223], v[84:87]
	v_mfma_f32_16x16x32_bf16 v[80:83], v[190:193], v[220:223], v[80:83]
	v_mfma_f32_16x16x32_bf16 v[68:71], v[182:185], v[228:231], v[68:71]
	v_mfma_f32_16x16x32_bf16 v[64:67], v[190:193], v[228:231], v[64:67]
	s_barrier
; #define PG8_STAGE(bufoff, gbase, voff) do { _Pragma("unroll") for (int _i = 0; _i < 2; ++_i) \
;         __builtin_amdgcn_global_load_lds((const unsigned*)((const char*)(gbase) + (voff)[_i]), (PG8_LAS unsigned*)(lds + (bufoff) + ldsw + _i * 8192), 16, 0, 0); } while (0)
; #define PG8_LDA(dst, b, h) do { _Pragma("unroll") for (int m = 0; m < 4; ++m) _Pragma("unroll") for (int k = 0; k < 2; ++k) dst[m][k] = *(const PG8_LAS bf16x8*)(lds + PG8_SA(b, h) + aoff + m * 2048 + k * 1024); } while (0)
; #define PG8_MMA(ai, bj, At, Bt) do { __builtin_amdgcn_s_setprio(1); _Pragma("unroll") for (int m = 0; m < 4; ++m) _Pragma("unroll") for (int n = 0; n < 2; ++n) _Pragma("unroll") for (int k = 0; k < 2; ++k) \
;         acc[ai][bj][m][n] = __builtin_amdgcn_mfma_f32_16x16x32_bf16(Bt[n][k], At[m][k], acc[ai][bj][m][n], 0, 0, 0); __builtin_amdgcn_s_setprio(0); } while (0)
; #define PG8_WAIT_V(n) asm volatile("s_waitcnt vmcnt(" #n ")" ::: "memory")
; #define PG8_WAIT_L(n) asm volatile("s_waitcnt lgkmcnt(" #n ")" ::: "memory")
; #define PG8_BAR __builtin_amdgcn_s_barrier()
; #define PG8_SCHED __builtin_amdgcn_sched_barrier(0)
; template <class Epi, class Sched, bool ALIGN_EPI = false, bool SP2 = false>
; __device__ __forceinline__ void gemm_phase(PG8_LAS unsigned char* lds, const Gemm g, const Sched& S, const Epi& E) {
;     ...
;         for (int t = 0; t < nt; t += 2) {
;             const bool last = (t == nt - 2);
;             const char* a1 = cA + (size_t)(t + 1) * kstep;
;             const char* a2 = last ? nA : cA + (size_t)(t + 2) * kstep; const char* b2 = last ? nB : cB + (size_t)(t + 2) * kstep;
;     ...
;             PG8_LDA(At, 1, 1); PG8_STAGE(PG8_SB(1, 0), b3, voffB); PG8_STAGE(PG8_SB(1, 1), b3 + hstep, voffB); PG8_STAGE(PG8_SA(1, 0), a3, voffA);
;             PG8_WAIT_V(8); PG8_WAIT_L(0); PG8_BAR; PG8_MMA(1, 0, At, B0); PG8_MMA(1, 1, At, B1); PG8_BAR; PG8_SCHED;
	s_setprio 0
	s_add_i32 s38, s44, s26
	v_lshl_add_u64 v[150:151], v[150:151], 0, s[90:91]
	s_mov_b32 m0, s38
	ds_read_b128 v[194:197], v141 offset:49152
	ds_read_b128 v[198:201], v141 offset:50176
	ds_read_b128 v[202:205], v141 offset:51200
	ds_read_b128 v[206:209], v141 offset:52224
	ds_read_b128 v[210:213], v141 offset:53248
	ds_read_b128 v[220:223], v141 offset:54272
	ds_read_b128 v[224:227], v141 offset:55296
	ds_read_b128 v[228:231], v141 offset:56320
	global_load_lds_dwordx4 v[150:151], off
	s_add_i32 m0, s38, 0x2000
	s_add_u32 s18, s18, 0x80080
	v_lshl_add_u64 v[150:151], v[214:215], 0, s[90:91]
	s_addc_u32 s19, s19, 0
	s_add_i32 s38, s45, s26
	global_load_lds_dwordx4 v[150:151], off
	v_lshl_add_u64 v[150:151], s[18:19], 0, v[152:153]
	s_mov_b32 m0, s38
	s_nop 0
	global_load_lds_dwordx4 v[150:151], off
	v_lshl_add_u64 v[150:151], s[18:19], 0, v[128:129]
	s_add_i32 m0, s38, 0x2000
	s_nop 0
	global_load_lds_dwordx4 v[150:151], off
	v_lshl_add_u64 v[150:151], v[232:233], 0, s[90:91]
	s_mov_b32 m0, s33
	s_nop 0
	global_load_lds_dwordx4 v[150:151], off
	v_lshl_add_u64 v[150:151], v[234:235], 0, s[90:91]
	s_mov_b32 m0, s40
	s_nop 0
	global_load_lds_dwordx4 v[150:151], off
	s_waitcnt vmcnt(8)
	s_waitcnt lgkmcnt(0)
	s_setprio 1
	s_barrier
	v_mfma_f32_16x16x32_bf16 v[60:63], v[142:145], v[194:197], v[60:63]
	v_mfma_f32_16x16x32_bf16 v[56:59], v[170:173], v[194:197], v[56:59]
	v_mfma_f32_16x16x32_bf16 v[44:47], v[142:145], v[202:205], v[44:47]
	v_mfma_f32_16x16x32_bf16 v[40:43], v[170:173], v[202:205], v[40:43]
	v_mfma_f32_16x16x32_bf16 v[28:31], v[142:145], v[210:213], v[28:31]
	v_mfma_f32_16x16x32_bf16 v[24:27], v[170:173], v[210:213], v[24:27]
	v_mfma_f32_16x16x32_bf16 v[12:15], v[142:145], v[224:227], v[12:15]
	v_mfma_f32_16x16x32_bf16 v[8:11], v[170:173], v[224:227], v[8:11]
	v_mfma_f32_16x16x32_bf16 v[60:63], v[146:149], v[198:201], v[60:63]
	v_mfma_f32_16x16x32_bf16 v[56:59], v[174:177], v[198:201], v[56:59]
	v_mfma_f32_16x16x32_bf16 v[44:47], v[146:149], v[206:209], v[44:47]
	v_mfma_f32_16x16x32_bf16 v[40:43], v[174:177], v[206:209], v[40:43]
	v_mfma_f32_16x16x32_bf16 v[28:31], v[146:149], v[220:223], v[28:31]
	v_mfma_f32_16x16x32_bf16 v[24:27], v[174:177], v[220:223], v[24:27]
	v_mfma_f32_16x16x32_bf16 v[12:15], v[146:149], v[228:231], v[12:15]
	v_mfma_f32_16x16x32_bf16 v[8:11], v[174:177], v[228:231], v[8:11]
	v_mfma_f32_16x16x32_bf16 v[52:55], v[178:181], v[194:197], v[52:55]
	v_mfma_f32_16x16x32_bf16 v[48:51], v[186:189], v[194:197], v[48:51]
	v_mfma_f32_16x16x32_bf16 v[36:39], v[178:181], v[202:205], v[36:39]
	v_mfma_f32_16x16x32_bf16 v[32:35], v[186:189], v[202:205], v[32:35]
	v_mfma_f32_16x16x32_bf16 v[20:23], v[178:181], v[210:213], v[20:23]
	v_mfma_f32_16x16x32_bf16 v[16:19], v[186:189], v[210:213], v[16:19]
	v_mfma_f32_16x16x32_bf16 v[4:7], v[178:181], v[224:227], v[4:7]
	v_mfma_f32_16x16x32_bf16 v[0:3], v[186:189], v[224:227], v[0:3]
	v_mfma_f32_16x16x32_bf16 v[52:55], v[182:185], v[198:201], v[52:55]
	v_mfma_f32_16x16x32_bf16 v[48:51], v[190:193], v[198:201], v[48:51]
	v_mfma_f32_16x16x32_bf16 v[36:39], v[182:185], v[206:209], v[36:39]
	v_mfma_f32_16x16x32_bf16 v[32:35], v[190:193], v[206:209], v[32:35]
	v_mfma_f32_16x16x32_bf16 v[20:23], v[182:185], v[220:223], v[20:23]
	v_mfma_f32_16x16x32_bf16 v[16:19], v[190:193], v[220:223], v[16:19]
	v_mfma_f32_16x16x32_bf16 v[4:7], v[182:185], v[228:231], v[4:7]
	v_mfma_f32_16x16x32_bf16 v[0:3], v[190:193], v[228:231], v[0:3]
	s_barrier
	s_setprio 0
	s_add_i32 s43, s43, 2
	s_add_u32 s16, s16, 0x100
	s_addc_u32 s17, s17, 0
	s_cmp_gt_u32 s43, 29
	s_cbranch_scc0 .LBB0_291
	s_cmpk_lt_u32 s25, 0x100
	s_cbranch_scc0 .LBB0_294
	s_barrier

; #define PG8_STAGE(bufoff, gbase, voff) do { _Pragma("unroll") for (int _i = 0; _i < 2; ++_i) \
;         __builtin_amdgcn_global_load_lds((const unsigned*)((const char*)(gbase) + (voff)[_i]), (PG8_LAS unsigned*)(lds + (bufoff) + ldsw + _i * 8192), 16, 0, 0); } while (0)
; #define PG8_LDA(dst, b, h) do { _Pragma("unroll") for (int m = 0; m < 4; ++m) _Pragma("unroll") for (int k = 0; k < 2; ++k) dst[m][k] = *(const PG8_LAS bf16x8*)(lds + PG8_SA(b, h) + aoff + m * 2048 + k * 1024); } while (0)
; #define PG8_LDB(dst, b, h) do { _Pragma("unroll") for (int n = 0; n < 2; ++n) _Pragma("unroll") for (int k = 0; k < 2; ++k) dst[n][k] = *(const PG8_LAS bf16x8*)(lds + PG8_SB(b, h) + boff + n * 2048 + k * 1024); } while (0)
; #define PG8_MMA(ai, bj, At, Bt) do { __builtin_amdgcn_s_setprio(1); _Pragma("unroll") for (int m = 0; m < 4; ++m) _Pragma("unroll") for (int n = 0; n < 2; ++n) _Pragma("unroll") for (int k = 0; k < 2; ++k) \
;         acc[ai][bj][m][n] = __builtin_amdgcn_mfma_f32_16x16x32_bf16(Bt[n][k], At[m][k], acc[ai][bj][m][n], 0, 0, 0); __builtin_amdgcn_s_setprio(0); } while (0)
; #define PG8_BAR __builtin_amdgcn_s_barrier()
; template <class Epi, class Sched, bool ALIGN_EPI = false, bool SP2 = false>
; __device__ __forceinline__ void gemm_phase(PG8_LAS unsigned char* lds, const Gemm g, const Sched& S, const Epi& E) {
;     ...
;         const bool has_next = S.next(ui + 1, nxt);
;         const char* nA = has_next ? (const char*)g.A + (size_t)nxt.pm * tstep : cA; const char* nB = has_next ? (const char*)g.Bt + (size_t)nxt.pn * tstep : cB;
;         for (int t = 0; t < nt; t += 2) {
;             const bool last = (t == nt - 2);
;             const char* a1 = cA + (size_t)(t + 1) * kstep;
;             const char* a2 = last ? nA : cA + (size_t)(t + 2) * kstep; const char* b2 = last ? nB : cB + (size_t)(t + 2) * kstep;
;             const char* a3 = a2 + kstep; const char* b3 = b2 + kstep;
;             if (last && has_next) S.a_ready(nxt);
;             if constexpr (SP2) {
;             PG8_LDB(B0, 0, 0); PG8_LDB(B1, 0, 1); PG8_SCHED; PG8_LDA(At, 0, 0); PG8_STAGE(PG8_SA(1, 1), a1 + hstep, voffA);
;             PG8_WAIT_V(8); PG8_WAIT_L(0); PG8_BAR; PG8_MMA(0, 0, At, B0); PG8_MMA(0, 1, At, B1); PG8_BAR; PG8_SCHED;
;             PG8_LDA(At, 0, 1); PG8_STAGE(PG8_SB(0, 0), b2, voffB); PG8_STAGE(PG8_SB(0, 1), b2 + hstep, voffB); PG8_STAGE(PG8_SA(0, 0), a2, voffA);
.LBB0_349:
	s_or_b32 s4, s48, 1
	s_add_i32 s48, s48, 2
	s_mov_b32 s49, s5
	s_lshl_b64 s[58:59], s[4:5], 7
	s_lshl_b64 s[82:83], s[48:49], 7
	s_add_u32 s4, s14, s82
	s_addc_u32 s33, s15, s83
	s_and_b64 s[56:57], s[54:55], exec
	s_cselect_b32 s57, s45, s33
	s_cselect_b32 s56, s44, s4
	s_add_u32 s4, s16, s82
	s_addc_u32 s33, s17, s83
	s_and_b64 s[54:55], s[54:55], exec
	s_cselect_b32 s55, s47, s33
	s_cselect_b32 s54, s46, s4
	s_add_i32 s4, 0, 0x10000
	v_add_u32_e32 v150, s4, v135
	s_add_i32 s33, 0, 0x14000
	ds_read_b128 v[138:141], v150
	ds_read_b128 v[142:145], v150 offset:1024
	ds_read_b128 v[146:149], v150 offset:2048
	ds_read_b128 v[170:173], v150 offset:3072
	v_add_u32_e32 v150, s33, v135
	ds_read_b128 v[174:177], v150
	ds_read_b128 v[178:181], v150 offset:1024
	ds_read_b128 v[182:185], v150 offset:2048
	ds_read_b128 v[186:189], v150 offset:3072
	s_add_u32 s58, s25, s58
	s_addc_u32 s59, s29, s59
	v_lshl_add_u64 v[150:151], s[58:59], 0, v[128:129]
	s_add_i32 m0, s69, 0xc000
	ds_read_b128 v[190:193], v137
	ds_read_b128 v[194:197], v137 offset:1024
	ds_read_b128 v[198:201], v137 offset:2048
	ds_read_b128 v[202:205], v137 offset:3072
	ds_read_b128 v[206:209], v137 offset:4096
	ds_read_b128 v[210:213], v137 offset:5120
	ds_read_b128 v[220:223], v137 offset:6144
	ds_read_b128 v[224:227], v137 offset:7168
	global_load_lds_dwordx4 v[150:151], off
	v_lshl_add_u64 v[150:151], s[58:59], 0, v[130:131]
	s_add_i32 m0, s69, 0xe000
	s_nop 0
	global_load_lds_dwordx4 v[150:151], off
	s_waitcnt vmcnt(8)
	s_waitcnt lgkmcnt(0)
	s_setprio 1
	s_barrier
	v_mfma_f32_16x16x32_bf16 v[124:127], v[138:141], v[190:193], v[124:127]
	v_mfma_f32_16x16x32_bf16 v[120:123], v[146:149], v[190:193], v[120:123]
	v_mfma_f32_16x16x32_bf16 v[116:119], v[138:141], v[198:201], v[116:119]
	v_mfma_f32_16x16x32_bf16 v[112:115], v[146:149], v[198:201], v[112:115]
	v_mfma_f32_16x16x32_bf16 v[108:111], v[138:141], v[206:209], v[108:111]
	v_mfma_f32_16x16x32_bf16 v[104:107], v[146:149], v[206:209], v[104:107]
	v_mfma_f32_16x16x32_bf16 v[100:103], v[138:141], v[220:223], v[100:103]
	v_mfma_f32_16x16x32_bf16 v[96:99], v[146:149], v[220:223], v[96:99]
	v_mfma_f32_16x16x32_bf16 v[124:127], v[142:145], v[194:197], v[124:127]
	v_mfma_f32_16x16x32_bf16 v[120:123], v[170:173], v[194:197], v[120:123]
	v_mfma_f32_16x16x32_bf16 v[116:119], v[142:145], v[202:205], v[116:119]
	v_mfma_f32_16x16x32_bf16 v[112:115], v[170:173], v[202:205], v[112:115]
	v_mfma_f32_16x16x32_bf16 v[108:111], v[142:145], v[210:213], v[108:111]
	v_mfma_f32_16x16x32_bf16 v[104:107], v[170:173], v[210:213], v[104:107]
	v_mfma_f32_16x16x32_bf16 v[100:103], v[142:145], v[224:227], v[100:103]
	v_mfma_f32_16x16x32_bf16 v[96:99], v[170:173], v[224:227], v[96:99]
	v_mfma_f32_16x16x32_bf16 v[92:95], v[174:177], v[190:193], v[92:95]
	v_mfma_f32_16x16x32_bf16 v[88:91], v[182:185], v[190:193], v[88:91]
	v_mfma_f32_16x16x32_bf16 v[84:87], v[174:177], v[198:201], v[84:87]
	v_mfma_f32_16x16x32_bf16 v[80:83], v[182:185], v[198:201], v[80:83]
	v_mfma_f32_16x16x32_bf16 v[76:79], v[174:177], v[206:209], v[76:79]
	v_mfma_f32_16x16x32_bf16 v[72:75], v[182:185], v[206:209], v[72:75]
	v_mfma_f32_16x16x32_bf16 v[68:71], v[174:177], v[220:223], v[68:71]
	v_mfma_f32_16x16x32_bf16 v[64:67], v[182:185], v[220:223], v[64:67]
	v_mfma_f32_16x16x32_bf16 v[92:95], v[178:181], v[194:197], v[92:95]
	v_mfma_f32_16x16x32_bf16 v[88:91], v[186:189], v[194:197], v[88:91]
	v_mfma_f32_16x16x32_bf16 v[84:87], v[178:181], v[202:205], v[84:87]
	v_mfma_f32_16x16x32_bf16 v[80:83], v[186:189], v[202:205], v[80:83]
	v_mfma_f32_16x16x32_bf16 v[76:79], v[178:181], v[210:213], v[76:79]
	v_mfma_f32_16x16x32_bf16 v[72:75], v[186:189], v[210:213], v[72:75]
	v_mfma_f32_16x16x32_bf16 v[68:71], v[178:181], v[224:227], v[68:71]
	v_mfma_f32_16x16x32_bf16 v[64:67], v[186:189], v[224:227], v[64:67]
	s_barrier
	s_setprio 0
	s_add_i32 s4, s4, s68
	v_lshl_add_u64 v[150:151], s[54:55], 0, v[152:153]
	s_mov_b32 m0, s4
	ds_read_b128 v[190:193], v137 offset:16384
	ds_read_b128 v[194:197], v137 offset:17408
	ds_read_b128 v[198:201], v137 offset:18432
	ds_read_b128 v[202:205], v137 offset:19456
	ds_read_b128 v[206:209], v137 offset:20480
	ds_read_b128 v[210:213], v137 offset:21504
	ds_read_b128 v[220:223], v137 offset:22528
	ds_read_b128 v[224:227], v137 offset:23552
	global_load_lds_dwordx4 v[150:151], off
	s_add_i32 m0, s4, 0x2000
	v_lshl_add_u64 v[214:215], s[54:55], 0, v[132:133]
	s_add_u32 s54, s54, s66
	s_addc_u32 s55, s55, 0
	s_add_i32 s4, s33, s68
	global_load_lds_dwordx4 v[214:215], off
	v_lshl_add_u64 v[228:229], s[54:55], 0, v[152:153]
	s_mov_b32 m0, s4
	v_lshl_add_u64 v[230:231], s[54:55], 0, v[132:133]
	global_load_lds_dwordx4 v[228:229], off
	s_add_i32 m0, s4, 0x2000
	v_lshl_add_u64 v[232:233], s[56:57], 0, v[128:129]
	global_load_lds_dwordx4 v[230:231], off
	s_mov_b32 m0, s69
	v_lshl_add_u64 v[234:235], s[56:57], 0, v[130:131]
	global_load_lds_dwordx4 v[232:233], off
	s_mov_b32 m0, s70
	s_nop 0
	global_load_lds_dwordx4 v[234:235], off
	s_waitcnt vmcnt(8)
	s_waitcnt lgkmcnt(0)
	s_setprio 1
	s_barrier
; #define PG8_STAGE(bufoff, gbase, voff) do { _Pragma("unroll") for (int _i = 0; _i < 2; ++_i) \
;         __builtin_amdgcn_global_load_lds((const unsigned*)((const char*)(gbase) + (voff)[_i]), (PG8_LAS unsigned*)(lds + (bufoff) + ldsw + _i * 8192), 16, 0, 0); } while (0)
; #define PG8_LDA(dst, b, h) do { _Pragma("unroll") for (int m = 0; m < 4; ++m) _Pragma("unroll") for (int k = 0; k < 2; ++k) dst[m][k] = *(const PG8_LAS bf16x8*)(lds + PG8_SA(b, h) + aoff + m * 2048 + k * 1024); } while (0)
; #define PG8_LDB(dst, b, h) do { _Pragma("unroll") for (int n = 0; n < 2; ++n) _Pragma("unroll") for (int k = 0; k < 2; ++k) dst[n][k] = *(const PG8_LAS bf16x8*)(lds + PG8_SB(b, h) + boff + n * 2048 + k * 1024); } while (0)
; #define PG8_MMA(ai, bj, At, Bt) do { __builtin_amdgcn_s_setprio(1); _Pragma("unroll") for (int m = 0; m < 4; ++m) _Pragma("unroll") for (int n = 0; n < 2; ++n) _Pragma("unroll") for (int k = 0; k < 2; ++k) \
;         acc[ai][bj][m][n] = __builtin_amdgcn_mfma_f32_16x16x32_bf16(Bt[n][k], At[m][k], acc[ai][bj][m][n], 0, 0, 0); __builtin_amdgcn_s_setprio(0); } while (0)
; #define PG8_WAIT_V(n) asm volatile("s_waitcnt vmcnt(" #n ")" ::: "memory")
; #define PG8_WAIT_L(n) asm volatile("s_waitcnt lgkmcnt(" #n ")" ::: "memory")
; #define PG8_BAR __builtin_amdgcn_s_barrier()
; #define PG8_SCHED __builtin_amdgcn_sched_barrier(0)
; template <class Epi, class Sched, bool ALIGN_EPI = false, bool SP2 = false>
; __device__ __forceinline__ void gemm_phase(PG8_LAS unsigned char* lds, const Gemm g, const Sched& S, const Epi& E) {
;     ...
;             PG8_WAIT_V(8); PG8_WAIT_L(0); PG8_BAR; PG8_MMA(1, 0, At, B0); PG8_MMA(1, 1, At, B1); PG8_BAR; PG8_SCHED;
;             PG8_LDB(B0, 1, 0); PG8_LDB(B1, 1, 1); PG8_SCHED; PG8_LDA(At, 1, 0); PG8_STAGE(PG8_SA(0, 1), a2 + hstep, voffA);
;             PG8_WAIT_V(8); PG8_WAIT_L(0); PG8_BAR; PG8_MMA(0, 0, At, B0); PG8_MMA(0, 1, At, B1); PG8_BAR; PG8_SCHED;
	v_mfma_f32_16x16x32_bf16 v[60:63], v[138:141], v[190:193], v[60:63]
	v_mfma_f32_16x16x32_bf16 v[56:59], v[146:149], v[190:193], v[56:59]
	v_mfma_f32_16x16x32_bf16 v[52:55], v[138:141], v[198:201], v[52:55]
	v_mfma_f32_16x16x32_bf16 v[48:51], v[146:149], v[198:201], v[48:51]
	v_mfma_f32_16x16x32_bf16 v[44:47], v[138:141], v[206:209], v[44:47]
	v_mfma_f32_16x16x32_bf16 v[40:43], v[146:149], v[206:209], v[40:43]
	v_mfma_f32_16x16x32_bf16 v[36:39], v[138:141], v[220:223], v[36:39]
	v_mfma_f32_16x16x32_bf16 v[32:35], v[146:149], v[220:223], v[32:35]
	v_mfma_f32_16x16x32_bf16 v[60:63], v[142:145], v[194:197], v[60:63]
	v_mfma_f32_16x16x32_bf16 v[56:59], v[170:173], v[194:197], v[56:59]
	v_mfma_f32_16x16x32_bf16 v[52:55], v[142:145], v[202:205], v[52:55]
	v_mfma_f32_16x16x32_bf16 v[48:51], v[170:173], v[202:205], v[48:51]
	v_mfma_f32_16x16x32_bf16 v[44:47], v[142:145], v[210:213], v[44:47]
	v_mfma_f32_16x16x32_bf16 v[40:43], v[170:173], v[210:213], v[40:43]
	v_mfma_f32_16x16x32_bf16 v[36:39], v[142:145], v[224:227], v[36:39]
	v_mfma_f32_16x16x32_bf16 v[32:35], v[170:173], v[224:227], v[32:35]
	v_mfma_f32_16x16x32_bf16 v[28:31], v[174:177], v[190:193], v[28:31]
	v_mfma_f32_16x16x32_bf16 v[24:27], v[182:185], v[190:193], v[24:27]
	v_mfma_f32_16x16x32_bf16 v[20:23], v[174:177], v[198:201], v[20:23]
	v_mfma_f32_16x16x32_bf16 v[16:19], v[182:185], v[198:201], v[16:19]
	v_mfma_f32_16x16x32_bf16 v[12:15], v[174:177], v[206:209], v[12:15]
	v_mfma_f32_16x16x32_bf16 v[8:11], v[182:185], v[206:209], v[8:11]
	v_mfma_f32_16x16x32_bf16 v[4:7], v[174:177], v[220:223], v[4:7]
	v_mfma_f32_16x16x32_bf16 v[0:3], v[182:185], v[220:223], v[0:3]
	v_mfma_f32_16x16x32_bf16 v[28:31], v[178:181], v[194:197], v[28:31]
	v_mfma_f32_16x16x32_bf16 v[24:27], v[186:189], v[194:197], v[24:27]
	v_mfma_f32_16x16x32_bf16 v[20:23], v[178:181], v[202:205], v[20:23]
	v_mfma_f32_16x16x32_bf16 v[16:19], v[186:189], v[202:205], v[16:19]
	v_mfma_f32_16x16x32_bf16 v[12:15], v[178:181], v[210:213], v[12:15]
	v_mfma_f32_16x16x32_bf16 v[8:11], v[186:189], v[210:213], v[8:11]
	v_mfma_f32_16x16x32_bf16 v[4:7], v[178:181], v[224:227], v[4:7]
	v_mfma_f32_16x16x32_bf16 v[0:3], v[186:189], v[224:227], v[0:3]
	s_barrier
	s_setprio 0
	s_add_i32 s4, 0, 0x18000
	s_add_i32 s33, 0, 0x1c000
	v_add_u32_e32 v170, s4, v135
	v_add_u32_e32 v186, s33, v135
	ds_read_b128 v[138:141], v170
	ds_read_b128 v[142:145], v170 offset:1024
	ds_read_b128 v[146:149], v170 offset:2048
	ds_read_b128 v[170:173], v170 offset:3072
	ds_read_b128 v[174:177], v186
	ds_read_b128 v[178:181], v186 offset:1024
	ds_read_b128 v[182:185], v186 offset:2048
	ds_read_b128 v[186:189], v186 offset:3072
	s_add_u32 s54, s56, s66
	s_addc_u32 s55, s57, 0
	s_mov_b32 m0, s71
	v_lshl_add_u64 v[236:237], s[54:55], 0, v[128:129]
	ds_read_b128 v[190:193], v137 offset:32768
	ds_read_b128 v[194:197], v137 offset:33792
	ds_read_b128 v[198:201], v137 offset:34816
	ds_read_b128 v[202:205], v137 offset:35840
	ds_read_b128 v[206:209], v137 offset:36864
	ds_read_b128 v[210:213], v137 offset:37888
	ds_read_b128 v[220:223], v137 offset:38912
	ds_read_b128 v[224:227], v137 offset:39936
	global_load_lds_dwordx4 v[236:237], off
	v_lshl_add_u64 v[236:237], s[54:55], 0, v[130:131]
	s_mov_b32 m0, s72
	s_nop 0
	global_load_lds_dwordx4 v[236:237], off
	s_waitcnt vmcnt(8)
	s_waitcnt lgkmcnt(0)
	s_setprio 1
	s_barrier
	v_mfma_f32_16x16x32_bf16 v[124:127], v[138:141], v[190:193], v[124:127]
	v_mfma_f32_16x16x32_bf16 v[120:123], v[146:149], v[190:193], v[120:123]
	v_mfma_f32_16x16x32_bf16 v[116:119], v[138:141], v[198:201], v[116:119]
	v_mfma_f32_16x16x32_bf16 v[112:115], v[146:149], v[198:201], v[112:115]
	v_mfma_f32_16x16x32_bf16 v[108:111], v[138:141], v[206:209], v[108:111]
	v_mfma_f32_16x16x32_bf16 v[104:107], v[146:149], v[206:209], v[104:107]
	v_mfma_f32_16x16x32_bf16 v[100:103], v[138:141], v[220:223], v[100:103]
	v_mfma_f32_16x16x32_bf16 v[96:99], v[146:149], v[220:223], v[96:99]
	v_mfma_f32_16x16x32_bf16 v[124:127], v[142:145], v[194:197], v[124:127]
	v_mfma_f32_16x16x32_bf16 v[120:123], v[170:173], v[194:197], v[120:123]
	v_mfma_f32_16x16x32_bf16 v[116:119], v[142:145], v[202:205], v[116:119]
	v_mfma_f32_16x16x32_bf16 v[112:115], v[170:173], v[202:205], v[112:115]
	v_mfma_f32_16x16x32_bf16 v[108:111], v[142:145], v[210:213], v[108:111]
	v_mfma_f32_16x16x32_bf16 v[104:107], v[170:173], v[210:213], v[104:107]
	v_mfma_f32_16x16x32_bf16 v[100:103], v[142:145], v[224:227], v[100:103]
	v_mfma_f32_16x16x32_bf16 v[96:99], v[170:173], v[224:227], v[96:99]
	v_mfma_f32_16x16x32_bf16 v[92:95], v[174:177], v[190:193], v[92:95]
	v_mfma_f32_16x16x32_bf16 v[88:91], v[182:185], v[190:193], v[88:91]
	v_mfma_f32_16x16x32_bf16 v[84:87], v[174:177], v[198:201], v[84:87]
	v_mfma_f32_16x16x32_bf16 v[80:83], v[182:185], v[198:201], v[80:83]
	v_mfma_f32_16x16x32_bf16 v[76:79], v[174:177], v[206:209], v[76:79]
	v_mfma_f32_16x16x32_bf16 v[72:75], v[182:185], v[206:209], v[72:75]
	v_mfma_f32_16x16x32_bf16 v[68:71], v[174:177], v[220:223], v[68:71]
	v_mfma_f32_16x16x32_bf16 v[64:67], v[182:185], v[220:223], v[64:67]
	v_mfma_f32_16x16x32_bf16 v[92:95], v[178:181], v[194:197], v[92:95]
	v_mfma_f32_16x16x32_bf16 v[88:91], v[186:189], v[194:197], v[88:91]
	v_mfma_f32_16x16x32_bf16 v[84:87], v[178:181], v[202:205], v[84:87]
	v_mfma_f32_16x16x32_bf16 v[80:83], v[186:189], v[202:205], v[80:83]
	v_mfma_f32_16x16x32_bf16 v[76:79], v[178:181], v[210:213], v[76:79]
	v_mfma_f32_16x16x32_bf16 v[72:75], v[186:189], v[210:213], v[72:75]
	v_mfma_f32_16x16x32_bf16 v[68:71], v[178:181], v[224:227], v[68:71]
	v_mfma_f32_16x16x32_bf16 v[64:67], v[186:189], v[224:227], v[64:67]
	s_barrier
; #define PG8_STAGE(bufoff, gbase, voff) do { _Pragma("unroll") for (int _i = 0; _i < 2; ++_i) \
;         __builtin_amdgcn_global_load_lds((const unsigned*)((const char*)(gbase) + (voff)[_i]), (PG8_LAS unsigned*)(lds + (bufoff) + ldsw + _i * 8192), 16, 0, 0); } while (0)
; #define PG8_LDA(dst, b, h) do { _Pragma("unroll") for (int m = 0; m < 4; ++m) _Pragma("unroll") for (int k = 0; k < 2; ++k) dst[m][k] = *(const PG8_LAS bf16x8*)(lds + PG8_SA(b, h) + aoff + m * 2048 + k * 1024); } while (0)
; #define PG8_MMA(ai, bj, At, Bt) do { __builtin_amdgcn_s_setprio(1); _Pragma("unroll") for (int m = 0; m < 4; ++m) _Pragma("unroll") for (int n = 0; n < 2; ++n) _Pragma("unroll") for (int k = 0; k < 2; ++k) \
;         acc[ai][bj][m][n] = __builtin_amdgcn_mfma_f32_16x16x32_bf16(Bt[n][k], At[m][k], acc[ai][bj][m][n], 0, 0, 0); __builtin_amdgcn_s_setprio(0); } while (0)
; #define PG8_WAIT_V(n) asm volatile("s_waitcnt vmcnt(" #n ")" ::: "memory")
; #define PG8_WAIT_L(n) asm volatile("s_waitcnt lgkmcnt(" #n ")" ::: "memory")
; #define PG8_BAR __builtin_amdgcn_s_barrier()
; #define PG8_SCHED __builtin_amdgcn_sched_barrier(0)
; template <class Epi, class Sched, bool ALIGN_EPI = false, bool SP2 = false>
; __device__ __forceinline__ void gemm_phase(PG8_LAS unsigned char* lds, const Gemm g, const Sched& S, const Epi& E) {
;     ...
;         for (int t = 0; t < nt; t += 2) {
;     ...
;             PG8_LDA(At, 1, 1); PG8_STAGE(PG8_SB(1, 0), b3, voffB); PG8_STAGE(PG8_SB(1, 1), b3 + hstep, voffB); PG8_STAGE(PG8_SA(1, 0), a3, voffA);
;             PG8_WAIT_V(8); PG8_WAIT_L(0); PG8_BAR; PG8_MMA(1, 0, At, B0); PG8_MMA(1, 1, At, B1); PG8_BAR; PG8_SCHED;
	s_setprio 0
	s_add_i32 s4, s4, s68
	v_lshl_add_u64 v[150:151], v[150:151], 0, s[90:91]
	s_mov_b32 m0, s4
	ds_read_b128 v[190:193], v137 offset:49152
	ds_read_b128 v[194:197], v137 offset:50176
	ds_read_b128 v[198:201], v137 offset:51200
	ds_read_b128 v[202:205], v137 offset:52224
	ds_read_b128 v[206:209], v137 offset:53248
	ds_read_b128 v[210:213], v137 offset:54272
	ds_read_b128 v[220:223], v137 offset:55296
	ds_read_b128 v[224:227], v137 offset:56320
	global_load_lds_dwordx4 v[150:151], off
	v_lshl_add_u64 v[150:151], v[214:215], 0, s[90:91]
	s_add_i32 m0, s4, 0x2000
	s_add_i32 s4, s33, s68
	global_load_lds_dwordx4 v[150:151], off
	v_lshl_add_u64 v[150:151], v[228:229], 0, s[90:91]
	s_mov_b32 m0, s4
	s_nop 0
	global_load_lds_dwordx4 v[150:151], off
	v_lshl_add_u64 v[150:151], v[230:231], 0, s[90:91]
	s_add_i32 m0, s4, 0x2000
	s_nop 0
	global_load_lds_dwordx4 v[150:151], off
	v_lshl_add_u64 v[150:151], v[232:233], 0, s[90:91]
	s_mov_b32 m0, s75
	s_nop 0
	global_load_lds_dwordx4 v[150:151], off
	v_lshl_add_u64 v[150:151], v[234:235], 0, s[90:91]
	s_mov_b32 m0, s76
	s_nop 0
	global_load_lds_dwordx4 v[150:151], off
	s_waitcnt vmcnt(8)
	s_waitcnt lgkmcnt(0)
	s_setprio 1
	s_barrier
	v_mfma_f32_16x16x32_bf16 v[60:63], v[138:141], v[190:193], v[60:63]
	v_mfma_f32_16x16x32_bf16 v[56:59], v[146:149], v[190:193], v[56:59]
	v_mfma_f32_16x16x32_bf16 v[52:55], v[138:141], v[198:201], v[52:55]
	v_mfma_f32_16x16x32_bf16 v[48:51], v[146:149], v[198:201], v[48:51]
	v_mfma_f32_16x16x32_bf16 v[44:47], v[138:141], v[206:209], v[44:47]
	v_mfma_f32_16x16x32_bf16 v[40:43], v[146:149], v[206:209], v[40:43]
	v_mfma_f32_16x16x32_bf16 v[36:39], v[138:141], v[220:223], v[36:39]
	v_mfma_f32_16x16x32_bf16 v[32:35], v[146:149], v[220:223], v[32:35]
	v_mfma_f32_16x16x32_bf16 v[60:63], v[142:145], v[194:197], v[60:63]
	v_mfma_f32_16x16x32_bf16 v[56:59], v[170:173], v[194:197], v[56:59]
	v_mfma_f32_16x16x32_bf16 v[52:55], v[142:145], v[202:205], v[52:55]
	v_mfma_f32_16x16x32_bf16 v[48:51], v[170:173], v[202:205], v[48:51]
	v_mfma_f32_16x16x32_bf16 v[44:47], v[142:145], v[210:213], v[44:47]
	v_mfma_f32_16x16x32_bf16 v[40:43], v[170:173], v[210:213], v[40:43]
	v_mfma_f32_16x16x32_bf16 v[36:39], v[142:145], v[224:227], v[36:39]
	v_mfma_f32_16x16x32_bf16 v[32:35], v[170:173], v[224:227], v[32:35]
	v_mfma_f32_16x16x32_bf16 v[28:31], v[174:177], v[190:193], v[28:31]
	v_mfma_f32_16x16x32_bf16 v[24:27], v[182:185], v[190:193], v[24:27]
	v_mfma_f32_16x16x32_bf16 v[20:23], v[174:177], v[198:201], v[20:23]
	v_mfma_f32_16x16x32_bf16 v[16:19], v[182:185], v[198:201], v[16:19]
	v_mfma_f32_16x16x32_bf16 v[12:15], v[174:177], v[206:209], v[12:15]
	v_mfma_f32_16x16x32_bf16 v[8:11], v[182:185], v[206:209], v[8:11]
	v_mfma_f32_16x16x32_bf16 v[4:7], v[174:177], v[220:223], v[4:7]
	v_mfma_f32_16x16x32_bf16 v[0:3], v[182:185], v[220:223], v[0:3]
	v_mfma_f32_16x16x32_bf16 v[28:31], v[178:181], v[194:197], v[28:31]
	v_mfma_f32_16x16x32_bf16 v[24:27], v[186:189], v[194:197], v[24:27]
	v_mfma_f32_16x16x32_bf16 v[20:23], v[178:181], v[202:205], v[20:23]
	v_mfma_f32_16x16x32_bf16 v[16:19], v[186:189], v[202:205], v[16:19]
	v_mfma_f32_16x16x32_bf16 v[12:15], v[178:181], v[210:213], v[12:15]
	v_mfma_f32_16x16x32_bf16 v[8:11], v[186:189], v[210:213], v[8:11]
	v_mfma_f32_16x16x32_bf16 v[4:7], v[178:181], v[224:227], v[4:7]
	v_mfma_f32_16x16x32_bf16 v[0:3], v[186:189], v[224:227], v[0:3]
	s_barrier
	s_setprio 0
	s_cmp_ge_u32 s48, s73
	s_cbranch_scc1 .LBB0_356

; #define PG8_STAGE(bufoff, gbase, voff) do { _Pragma("unroll") for (int _i = 0; _i < 2; ++_i) \
;         __builtin_amdgcn_global_load_lds((const unsigned*)((const char*)(gbase) + (voff)[_i]), (PG8_LAS unsigned*)(lds + (bufoff) + ldsw + _i * 8192), 16, 0, 0); } while (0)
; #define PG8_LDA(dst, b, h) do { _Pragma("unroll") for (int m = 0; m < 4; ++m) _Pragma("unroll") for (int k = 0; k < 2; ++k) dst[m][k] = *(const PG8_LAS bf16x8*)(lds + PG8_SA(b, h) + aoff + m * 2048 + k * 1024); } while (0)
; #define PG8_LDB(dst, b, h) do { _Pragma("unroll") for (int n = 0; n < 2; ++n) _Pragma("unroll") for (int k = 0; k < 2; ++k) dst[n][k] = *(const PG8_LAS bf16x8*)(lds + PG8_SB(b, h) + boff + n * 2048 + k * 1024); } while (0)
; #define PG8_MMA(ai, bj, At, Bt) do { __builtin_amdgcn_s_setprio(1); _Pragma("unroll") for (int m = 0; m < 4; ++m) _Pragma("unroll") for (int n = 0; n < 2; ++n) _Pragma("unroll") for (int k = 0; k < 2; ++k) \
;         acc[ai][bj][m][n] = __builtin_amdgcn_mfma_f32_16x16x32_bf16(Bt[n][k], At[m][k], acc[ai][bj][m][n], 0, 0, 0); __builtin_amdgcn_s_setprio(0); } while (0)
; #define PG8_BAR __builtin_amdgcn_s_barrier()
; template <class Epi, class Sched, bool ALIGN_EPI = false, bool SP2 = false>
; __device__ __forceinline__ void gemm_phase(PG8_LAS unsigned char* lds, const Gemm g, const Sched& S, const Epi& E) {
;     ...
;         const bool has_next = S.next(ui + 1, nxt);
;         const char* nA = has_next ? (const char*)g.A + (size_t)nxt.pm * tstep : cA; const char* nB = has_next ? (const char*)g.Bt + (size_t)nxt.pn * tstep : cB;
;         for (int t = 0; t < nt; t += 2) {
;             const bool last = (t == nt - 2);
;             const char* a1 = cA + (size_t)(t + 1) * kstep;
;             const char* a2 = last ? nA : cA + (size_t)(t + 2) * kstep; const char* b2 = last ? nB : cB + (size_t)(t + 2) * kstep;
;             const char* a3 = a2 + kstep; const char* b3 = b2 + kstep;
;             if (last && has_next) S.a_ready(nxt);
;             if constexpr (SP2) {
;             PG8_LDB(B0, 0, 0); PG8_LDB(B1, 0, 1); PG8_SCHED; PG8_LDA(At, 0, 0); PG8_STAGE(PG8_SA(1, 1), a1 + hstep, voffA);
;             PG8_WAIT_V(8); PG8_WAIT_L(0); PG8_BAR; PG8_MMA(0, 0, At, B0); PG8_MMA(0, 1, At, B1); PG8_BAR; PG8_SCHED;
;             PG8_LDA(At, 0, 1); PG8_STAGE(PG8_SB(0, 0), b2, voffB); PG8_STAGE(PG8_SB(0, 1), b2 + hstep, voffB); PG8_STAGE(PG8_SA(0, 0), a2, voffA);
.LBB0_431:
	s_add_u32 s54, s42, s52
	s_addc_u32 s55, s43, s53
	s_add_u32 s54, s54, 0x100
	s_addc_u32 s55, s55, 0
	s_add_u32 s75, s29, s52
	s_addc_u32 s76, s33, s53
	s_cmpk_eq_i32 s52, 0xf00
	s_cselect_b32 s57, s25, s55
	s_cselect_b32 s56, s47, s54
	s_cselect_b32 s55, s45, s76
	s_cselect_b32 s54, s73, s75
	s_add_i32 s75, 0, 0x10000
	v_add_u32_e32 v152, s75, v145
	s_add_i32 s78, 0, 0x14000
	ds_read_b128 v[148:151], v152
	ds_read_b128 v[170:173], v152 offset:1024
	ds_read_b128 v[174:177], v152 offset:2048
	ds_read_b128 v[178:181], v152 offset:3072
	v_add_u32_e32 v152, s78, v145
	ds_read_b128 v[182:185], v152
	ds_read_b128 v[186:189], v152 offset:1024
	ds_read_b128 v[190:193], v152 offset:2048
	ds_read_b128 v[194:197], v152 offset:3072
	s_add_u32 s76, s42, s52
	s_addc_u32 s77, s43, s53
	s_add_u32 s76, s76, 0x80080
	s_addc_u32 s77, s77, 0
	s_add_i32 m0, s15, 0xc000
	ds_read_b128 v[198:201], v147
	ds_read_b128 v[202:205], v147 offset:1024
	ds_read_b128 v[206:209], v147 offset:2048
	ds_read_b128 v[210:213], v147 offset:3072
	ds_read_b128 v[220:223], v147 offset:4096
	ds_read_b128 v[224:227], v147 offset:5120
	ds_read_b128 v[228:231], v147 offset:6144
	ds_read_b128 v[232:235], v147 offset:7168
	global_load_lds_dwordx4 v136, s[76:77]
	s_add_i32 m0, s15, 0xe000
	s_nop 0
	global_load_lds_dwordx4 v138, s[76:77]
	s_waitcnt vmcnt(8)
	s_waitcnt lgkmcnt(0)
	s_setprio 1
	s_barrier
	v_mfma_f32_16x16x32_bf16 v[124:127], v[148:151], v[198:201], v[124:127]
	v_mfma_f32_16x16x32_bf16 v[120:123], v[174:177], v[198:201], v[120:123]
	v_mfma_f32_16x16x32_bf16 v[116:119], v[148:151], v[206:209], v[116:119]
	v_mfma_f32_16x16x32_bf16 v[112:115], v[174:177], v[206:209], v[112:115]
	v_mfma_f32_16x16x32_bf16 v[108:111], v[148:151], v[220:223], v[108:111]
	v_mfma_f32_16x16x32_bf16 v[104:107], v[174:177], v[220:223], v[104:107]
	v_mfma_f32_16x16x32_bf16 v[100:103], v[148:151], v[228:231], v[100:103]
	v_mfma_f32_16x16x32_bf16 v[96:99], v[174:177], v[228:231], v[96:99]
	v_mfma_f32_16x16x32_bf16 v[124:127], v[170:173], v[202:205], v[124:127]
	v_mfma_f32_16x16x32_bf16 v[120:123], v[178:181], v[202:205], v[120:123]
	v_mfma_f32_16x16x32_bf16 v[116:119], v[170:173], v[210:213], v[116:119]
	v_mfma_f32_16x16x32_bf16 v[112:115], v[178:181], v[210:213], v[112:115]
	v_mfma_f32_16x16x32_bf16 v[108:111], v[170:173], v[224:227], v[108:111]
	v_mfma_f32_16x16x32_bf16 v[104:107], v[178:181], v[224:227], v[104:107]
	v_mfma_f32_16x16x32_bf16 v[100:103], v[170:173], v[232:235], v[100:103]
	v_mfma_f32_16x16x32_bf16 v[96:99], v[178:181], v[232:235], v[96:99]
	v_mfma_f32_16x16x32_bf16 v[92:95], v[182:185], v[198:201], v[92:95]
	v_mfma_f32_16x16x32_bf16 v[88:91], v[190:193], v[198:201], v[88:91]
	v_mfma_f32_16x16x32_bf16 v[84:87], v[182:185], v[206:209], v[84:87]
	v_mfma_f32_16x16x32_bf16 v[80:83], v[190:193], v[206:209], v[80:83]
	v_mfma_f32_16x16x32_bf16 v[76:79], v[182:185], v[220:223], v[76:79]
	v_mfma_f32_16x16x32_bf16 v[72:75], v[190:193], v[220:223], v[72:75]
	v_mfma_f32_16x16x32_bf16 v[68:71], v[182:185], v[228:231], v[68:71]
	v_mfma_f32_16x16x32_bf16 v[64:67], v[190:193], v[228:231], v[64:67]
	v_mfma_f32_16x16x32_bf16 v[92:95], v[186:189], v[202:205], v[92:95]
	v_mfma_f32_16x16x32_bf16 v[88:91], v[194:197], v[202:205], v[88:91]
	v_mfma_f32_16x16x32_bf16 v[84:87], v[186:189], v[210:213], v[84:87]
	v_mfma_f32_16x16x32_bf16 v[80:83], v[194:197], v[210:213], v[80:83]
	v_mfma_f32_16x16x32_bf16 v[76:79], v[186:189], v[224:227], v[76:79]
	v_mfma_f32_16x16x32_bf16 v[72:75], v[194:197], v[224:227], v[72:75]
	v_mfma_f32_16x16x32_bf16 v[68:71], v[186:189], v[232:235], v[68:71]
	v_mfma_f32_16x16x32_bf16 v[64:67], v[194:197], v[232:235], v[64:67]
	s_barrier
	s_setprio 0
	s_add_i32 s75, s75, s65
	s_mov_b32 m0, s75
	ds_read_b128 v[198:201], v147 offset:16384
	ds_read_b128 v[202:205], v147 offset:17408
	ds_read_b128 v[206:209], v147 offset:18432
	ds_read_b128 v[210:213], v147 offset:19456
	ds_read_b128 v[220:223], v147 offset:20480
	ds_read_b128 v[224:227], v147 offset:21504
	ds_read_b128 v[228:231], v147 offset:22528
	ds_read_b128 v[232:235], v147 offset:23552
	global_load_lds_dwordx4 v130, s[54:55]
	s_add_i32 m0, s75, 0x2000
	s_add_u32 s76, s54, 0x80000
	s_addc_u32 s77, s55, 0
	s_add_i32 s75, s78, s65
	global_load_lds_dwordx4 v134, s[54:55]
	s_mov_b32 m0, s75
	s_nop 0
	global_load_lds_dwordx4 v130, s[76:77]
	s_add_i32 m0, s75, 0x2000
	s_nop 0
	global_load_lds_dwordx4 v134, s[76:77]
	s_mov_b32 m0, s15
	s_nop 0
	global_load_lds_dwordx4 v128, s[56:57]
	s_mov_b32 m0, s17
	s_nop 0
	global_load_lds_dwordx4 v132, s[56:57]
	s_waitcnt vmcnt(8)
	s_waitcnt lgkmcnt(0)
	s_setprio 1
	s_barrier
; #define PG8_STAGE(bufoff, gbase, voff) do { _Pragma("unroll") for (int _i = 0; _i < 2; ++_i) \
;         __builtin_amdgcn_global_load_lds((const unsigned*)((const char*)(gbase) + (voff)[_i]), (PG8_LAS unsigned*)(lds + (bufoff) + ldsw + _i * 8192), 16, 0, 0); } while (0)
; #define PG8_LDA(dst, b, h) do { _Pragma("unroll") for (int m = 0; m < 4; ++m) _Pragma("unroll") for (int k = 0; k < 2; ++k) dst[m][k] = *(const PG8_LAS bf16x8*)(lds + PG8_SA(b, h) + aoff + m * 2048 + k * 1024); } while (0)
; #define PG8_LDB(dst, b, h) do { _Pragma("unroll") for (int n = 0; n < 2; ++n) _Pragma("unroll") for (int k = 0; k < 2; ++k) dst[n][k] = *(const PG8_LAS bf16x8*)(lds + PG8_SB(b, h) + boff + n * 2048 + k * 1024); } while (0)
; #define PG8_MMA(ai, bj, At, Bt) do { __builtin_amdgcn_s_setprio(1); _Pragma("unroll") for (int m = 0; m < 4; ++m) _Pragma("unroll") for (int n = 0; n < 2; ++n) _Pragma("unroll") for (int k = 0; k < 2; ++k) \
;         acc[ai][bj][m][n] = __builtin_amdgcn_mfma_f32_16x16x32_bf16(Bt[n][k], At[m][k], acc[ai][bj][m][n], 0, 0, 0); __builtin_amdgcn_s_setprio(0); } while (0)
; #define PG8_WAIT_V(n) asm volatile("s_waitcnt vmcnt(" #n ")" ::: "memory")
; #define PG8_WAIT_L(n) asm volatile("s_waitcnt lgkmcnt(" #n ")" ::: "memory")
; #define PG8_BAR __builtin_amdgcn_s_barrier()
; #define PG8_SCHED __builtin_amdgcn_sched_barrier(0)
; template <class Epi, class Sched, bool ALIGN_EPI = false, bool SP2 = false>
; __device__ __forceinline__ void gemm_phase(PG8_LAS unsigned char* lds, const Gemm g, const Sched& S, const Epi& E) {
;     ...
;             PG8_WAIT_V(8); PG8_WAIT_L(0); PG8_BAR; PG8_MMA(1, 0, At, B0); PG8_MMA(1, 1, At, B1); PG8_BAR; PG8_SCHED;
;             PG8_LDB(B0, 1, 0); PG8_LDB(B1, 1, 1); PG8_SCHED; PG8_LDA(At, 1, 0); PG8_STAGE(PG8_SA(0, 1), a2 + hstep, voffA);
;             PG8_WAIT_V(8); PG8_WAIT_L(0); PG8_BAR; PG8_MMA(0, 0, At, B0); PG8_MMA(0, 1, At, B1); PG8_BAR; PG8_SCHED;
	v_mfma_f32_16x16x32_bf16 v[60:63], v[148:151], v[198:201], v[60:63]
	v_mfma_f32_16x16x32_bf16 v[56:59], v[174:177], v[198:201], v[56:59]
	v_mfma_f32_16x16x32_bf16 v[52:55], v[148:151], v[206:209], v[52:55]
	v_mfma_f32_16x16x32_bf16 v[48:51], v[174:177], v[206:209], v[48:51]
	v_mfma_f32_16x16x32_bf16 v[44:47], v[148:151], v[220:223], v[44:47]
	v_mfma_f32_16x16x32_bf16 v[40:43], v[174:177], v[220:223], v[40:43]
	v_mfma_f32_16x16x32_bf16 v[36:39], v[148:151], v[228:231], v[36:39]
	v_mfma_f32_16x16x32_bf16 v[32:35], v[174:177], v[228:231], v[32:35]
	v_mfma_f32_16x16x32_bf16 v[60:63], v[170:173], v[202:205], v[60:63]
	v_mfma_f32_16x16x32_bf16 v[56:59], v[178:181], v[202:205], v[56:59]
	v_mfma_f32_16x16x32_bf16 v[52:55], v[170:173], v[210:213], v[52:55]
	v_mfma_f32_16x16x32_bf16 v[48:51], v[178:181], v[210:213], v[48:51]
	v_mfma_f32_16x16x32_bf16 v[44:47], v[170:173], v[224:227], v[44:47]
	v_mfma_f32_16x16x32_bf16 v[40:43], v[178:181], v[224:227], v[40:43]
	v_mfma_f32_16x16x32_bf16 v[36:39], v[170:173], v[232:235], v[36:39]
	v_mfma_f32_16x16x32_bf16 v[32:35], v[178:181], v[232:235], v[32:35]
	v_mfma_f32_16x16x32_bf16 v[28:31], v[182:185], v[198:201], v[28:31]
	v_mfma_f32_16x16x32_bf16 v[24:27], v[190:193], v[198:201], v[24:27]
	v_mfma_f32_16x16x32_bf16 v[20:23], v[182:185], v[206:209], v[20:23]
	v_mfma_f32_16x16x32_bf16 v[16:19], v[190:193], v[206:209], v[16:19]
	v_mfma_f32_16x16x32_bf16 v[12:15], v[182:185], v[220:223], v[12:15]
	v_mfma_f32_16x16x32_bf16 v[8:11], v[190:193], v[220:223], v[8:11]
	v_mfma_f32_16x16x32_bf16 v[4:7], v[182:185], v[228:231], v[4:7]
	v_mfma_f32_16x16x32_bf16 v[0:3], v[190:193], v[228:231], v[0:3]
	v_mfma_f32_16x16x32_bf16 v[28:31], v[186:189], v[202:205], v[28:31]
	v_mfma_f32_16x16x32_bf16 v[24:27], v[194:197], v[202:205], v[24:27]
	v_mfma_f32_16x16x32_bf16 v[20:23], v[186:189], v[210:213], v[20:23]
	v_mfma_f32_16x16x32_bf16 v[16:19], v[194:197], v[210:213], v[16:19]
	v_mfma_f32_16x16x32_bf16 v[12:15], v[186:189], v[224:227], v[12:15]
	v_mfma_f32_16x16x32_bf16 v[8:11], v[194:197], v[224:227], v[8:11]
	v_mfma_f32_16x16x32_bf16 v[4:7], v[186:189], v[232:235], v[4:7]
	v_mfma_f32_16x16x32_bf16 v[0:3], v[194:197], v[232:235], v[0:3]
	s_barrier
	s_setprio 0
	s_add_i32 s75, 0, 0x18000
	v_add_u32_e32 v152, s75, v145
	s_add_i32 s76, 0, 0x1c000
	ds_read_b128 v[148:151], v152
	ds_read_b128 v[170:173], v152 offset:1024
	ds_read_b128 v[174:177], v152 offset:2048
	ds_read_b128 v[178:181], v152 offset:3072
	v_add_u32_e32 v152, s76, v145
	ds_read_b128 v[182:185], v152
	ds_read_b128 v[186:189], v152 offset:1024
	ds_read_b128 v[190:193], v152 offset:2048
	ds_read_b128 v[194:197], v152 offset:3072
	s_add_u32 s56, s56, 0x80000
	s_addc_u32 s57, s57, 0
	s_mov_b32 m0, s68
	ds_read_b128 v[198:201], v147 offset:32768
	ds_read_b128 v[202:205], v147 offset:33792
	ds_read_b128 v[206:209], v147 offset:34816
	ds_read_b128 v[210:213], v147 offset:35840
	ds_read_b128 v[220:223], v147 offset:36864
	ds_read_b128 v[224:227], v147 offset:37888
	ds_read_b128 v[228:231], v147 offset:38912
	ds_read_b128 v[232:235], v147 offset:39936
	global_load_lds_dwordx4 v128, s[56:57]
	s_mov_b32 m0, s69
	s_nop 0
	global_load_lds_dwordx4 v132, s[56:57]
	s_waitcnt vmcnt(8)
	s_waitcnt lgkmcnt(0)
	s_setprio 1
	s_barrier
	v_mfma_f32_16x16x32_bf16 v[124:127], v[148:151], v[198:201], v[124:127]
	v_mfma_f32_16x16x32_bf16 v[120:123], v[174:177], v[198:201], v[120:123]
	v_mfma_f32_16x16x32_bf16 v[116:119], v[148:151], v[206:209], v[116:119]
	v_mfma_f32_16x16x32_bf16 v[112:115], v[174:177], v[206:209], v[112:115]
	v_mfma_f32_16x16x32_bf16 v[108:111], v[148:151], v[220:223], v[108:111]
	v_mfma_f32_16x16x32_bf16 v[104:107], v[174:177], v[220:223], v[104:107]
	v_mfma_f32_16x16x32_bf16 v[100:103], v[148:151], v[228:231], v[100:103]
	v_mfma_f32_16x16x32_bf16 v[96:99], v[174:177], v[228:231], v[96:99]
	v_mfma_f32_16x16x32_bf16 v[124:127], v[170:173], v[202:205], v[124:127]
	v_mfma_f32_16x16x32_bf16 v[120:123], v[178:181], v[202:205], v[120:123]
	v_mfma_f32_16x16x32_bf16 v[116:119], v[170:173], v[210:213], v[116:119]
	v_mfma_f32_16x16x32_bf16 v[112:115], v[178:181], v[210:213], v[112:115]
	v_mfma_f32_16x16x32_bf16 v[108:111], v[170:173], v[224:227], v[108:111]
	v_mfma_f32_16x16x32_bf16 v[104:107], v[178:181], v[224:227], v[104:107]
	v_mfma_f32_16x16x32_bf16 v[100:103], v[170:173], v[232:235], v[100:103]
	v_mfma_f32_16x16x32_bf16 v[96:99], v[178:181], v[232:235], v[96:99]
	v_mfma_f32_16x16x32_bf16 v[92:95], v[182:185], v[198:201], v[92:95]
	v_mfma_f32_16x16x32_bf16 v[88:91], v[190:193], v[198:201], v[88:91]
	v_mfma_f32_16x16x32_bf16 v[84:87], v[182:185], v[206:209], v[84:87]
	v_mfma_f32_16x16x32_bf16 v[80:83], v[190:193], v[206:209], v[80:83]
	v_mfma_f32_16x16x32_bf16 v[76:79], v[182:185], v[220:223], v[76:79]
	v_mfma_f32_16x16x32_bf16 v[72:75], v[190:193], v[220:223], v[72:75]
	v_mfma_f32_16x16x32_bf16 v[68:71], v[182:185], v[228:231], v[68:71]
	v_mfma_f32_16x16x32_bf16 v[64:67], v[190:193], v[228:231], v[64:67]
	v_mfma_f32_16x16x32_bf16 v[92:95], v[186:189], v[202:205], v[92:95]
	v_mfma_f32_16x16x32_bf16 v[88:91], v[194:197], v[202:205], v[88:91]
	v_mfma_f32_16x16x32_bf16 v[84:87], v[186:189], v[210:213], v[84:87]
	v_mfma_f32_16x16x32_bf16 v[80:83], v[194:197], v[210:213], v[80:83]
	v_mfma_f32_16x16x32_bf16 v[76:79], v[186:189], v[224:227], v[76:79]
	v_mfma_f32_16x16x32_bf16 v[72:75], v[194:197], v[224:227], v[72:75]
	v_mfma_f32_16x16x32_bf16 v[68:71], v[186:189], v[232:235], v[68:71]
	v_mfma_f32_16x16x32_bf16 v[64:67], v[194:197], v[232:235], v[64:67]
	s_barrier
; #define PG8_STAGE(bufoff, gbase, voff) do { _Pragma("unroll") for (int _i = 0; _i < 2; ++_i) \
;         __builtin_amdgcn_global_load_lds((const unsigned*)((const char*)(gbase) + (voff)[_i]), (PG8_LAS unsigned*)(lds + (bufoff) + ldsw + _i * 8192), 16, 0, 0); } while (0)
; #define PG8_LDA(dst, b, h) do { _Pragma("unroll") for (int m = 0; m < 4; ++m) _Pragma("unroll") for (int k = 0; k < 2; ++k) dst[m][k] = *(const PG8_LAS bf16x8*)(lds + PG8_SA(b, h) + aoff + m * 2048 + k * 1024); } while (0)
; #define PG8_MMA(ai, bj, At, Bt) do { __builtin_amdgcn_s_setprio(1); _Pragma("unroll") for (int m = 0; m < 4; ++m) _Pragma("unroll") for (int n = 0; n < 2; ++n) _Pragma("unroll") for (int k = 0; k < 2; ++k) \
;         acc[ai][bj][m][n] = __builtin_amdgcn_mfma_f32_16x16x32_bf16(Bt[n][k], At[m][k], acc[ai][bj][m][n], 0, 0, 0); __builtin_amdgcn_s_setprio(0); } while (0)
; #define PG8_WAIT_V(n) asm volatile("s_waitcnt vmcnt(" #n ")" ::: "memory")
; #define PG8_WAIT_L(n) asm volatile("s_waitcnt lgkmcnt(" #n ")" ::: "memory")
; #define PG8_BAR __builtin_amdgcn_s_barrier()
; #define PG8_SCHED __builtin_amdgcn_sched_barrier(0)
; template <class Epi, class Sched, bool ALIGN_EPI = false, bool SP2 = false>
; __device__ __forceinline__ void gemm_phase(PG8_LAS unsigned char* lds, const Gemm g, const Sched& S, const Epi& E) {
;     ...
;         for (int t = 0; t < nt; t += 2) {
;     ...
;             PG8_LDA(At, 1, 1); PG8_STAGE(PG8_SB(1, 0), b3, voffB); PG8_STAGE(PG8_SB(1, 1), b3 + hstep, voffB); PG8_STAGE(PG8_SA(1, 0), a3, voffA);
;             PG8_WAIT_V(8); PG8_WAIT_L(0); PG8_BAR; PG8_MMA(1, 0, At, B0); PG8_MMA(1, 1, At, B1); PG8_BAR; PG8_SCHED;
	s_setprio 0
	s_add_i32 s78, s75, s65
	s_add_u32 s54, s54, 0x80
	s_addc_u32 s55, s55, 0
	s_mov_b32 m0, s78
	ds_read_b128 v[198:201], v147 offset:49152
	ds_read_b128 v[202:205], v147 offset:50176
	ds_read_b128 v[206:209], v147 offset:51200
	ds_read_b128 v[210:213], v147 offset:52224
	ds_read_b128 v[220:223], v147 offset:53248
	ds_read_b128 v[224:227], v147 offset:54272
	ds_read_b128 v[228:231], v147 offset:55296
	ds_read_b128 v[232:235], v147 offset:56320
	global_load_lds_dwordx4 v130, s[54:55]
	s_add_i32 m0, s78, 0x2000
	s_add_i32 s78, s76, s65
	global_load_lds_dwordx4 v134, s[54:55]
	s_add_u32 s54, s54, 0x80000
	s_addc_u32 s55, s55, 0
	s_mov_b32 m0, s78
	s_nop 0
	global_load_lds_dwordx4 v130, s[54:55]
	s_add_i32 m0, s78, 0x2000
	s_sub_u32 s56, s56, 0x7ff80
	s_subb_u32 s57, s57, 0
	global_load_lds_dwordx4 v134, s[54:55]
	s_mov_b32 m0, s70
	s_nop 0
	global_load_lds_dwordx4 v128, s[56:57]
	s_mov_b32 m0, s71
	s_nop 0
	global_load_lds_dwordx4 v132, s[56:57]
	s_waitcnt vmcnt(8)
	s_waitcnt lgkmcnt(0)
	s_setprio 1
	s_barrier
	v_mfma_f32_16x16x32_bf16 v[60:63], v[148:151], v[198:201], v[60:63]
	v_mfma_f32_16x16x32_bf16 v[56:59], v[174:177], v[198:201], v[56:59]
	v_mfma_f32_16x16x32_bf16 v[52:55], v[148:151], v[206:209], v[52:55]
	v_mfma_f32_16x16x32_bf16 v[48:51], v[174:177], v[206:209], v[48:51]
	v_mfma_f32_16x16x32_bf16 v[44:47], v[148:151], v[220:223], v[44:47]
	v_mfma_f32_16x16x32_bf16 v[40:43], v[174:177], v[220:223], v[40:43]
	v_mfma_f32_16x16x32_bf16 v[36:39], v[148:151], v[228:231], v[36:39]
	v_mfma_f32_16x16x32_bf16 v[32:35], v[174:177], v[228:231], v[32:35]
	v_mfma_f32_16x16x32_bf16 v[60:63], v[170:173], v[202:205], v[60:63]
	v_mfma_f32_16x16x32_bf16 v[56:59], v[178:181], v[202:205], v[56:59]
	v_mfma_f32_16x16x32_bf16 v[52:55], v[170:173], v[210:213], v[52:55]
	v_mfma_f32_16x16x32_bf16 v[48:51], v[178:181], v[210:213], v[48:51]
	v_mfma_f32_16x16x32_bf16 v[44:47], v[170:173], v[224:227], v[44:47]
	v_mfma_f32_16x16x32_bf16 v[40:43], v[178:181], v[224:227], v[40:43]
	v_mfma_f32_16x16x32_bf16 v[36:39], v[170:173], v[232:235], v[36:39]
	v_mfma_f32_16x16x32_bf16 v[32:35], v[178:181], v[232:235], v[32:35]
	v_mfma_f32_16x16x32_bf16 v[28:31], v[182:185], v[198:201], v[28:31]
	v_mfma_f32_16x16x32_bf16 v[24:27], v[190:193], v[198:201], v[24:27]
	v_mfma_f32_16x16x32_bf16 v[20:23], v[182:185], v[206:209], v[20:23]
	v_mfma_f32_16x16x32_bf16 v[16:19], v[190:193], v[206:209], v[16:19]
	v_mfma_f32_16x16x32_bf16 v[12:15], v[182:185], v[220:223], v[12:15]
	v_mfma_f32_16x16x32_bf16 v[8:11], v[190:193], v[220:223], v[8:11]
	v_mfma_f32_16x16x32_bf16 v[4:7], v[182:185], v[228:231], v[4:7]
	v_mfma_f32_16x16x32_bf16 v[0:3], v[190:193], v[228:231], v[0:3]
	v_mfma_f32_16x16x32_bf16 v[28:31], v[186:189], v[202:205], v[28:31]
	v_mfma_f32_16x16x32_bf16 v[24:27], v[194:197], v[202:205], v[24:27]
	v_mfma_f32_16x16x32_bf16 v[20:23], v[186:189], v[210:213], v[20:23]
	v_mfma_f32_16x16x32_bf16 v[16:19], v[194:197], v[210:213], v[16:19]
	v_mfma_f32_16x16x32_bf16 v[12:15], v[186:189], v[224:227], v[12:15]
	v_mfma_f32_16x16x32_bf16 v[8:11], v[194:197], v[224:227], v[8:11]
	v_mfma_f32_16x16x32_bf16 v[4:7], v[186:189], v[232:235], v[4:7]
	v_mfma_f32_16x16x32_bf16 v[0:3], v[194:197], v[232:235], v[0:3]
	s_barrier
	s_setprio 0
	s_add_i32 s74, s74, 2
	s_add_u32 s52, s52, 0x100
	s_addc_u32 s53, s53, 0
	s_cmp_gt_u32 s74, 29
	s_cbranch_scc0 .LBB0_431
	s_and_b64 vcc, exec, s[26:27]
	s_cbranch_vccz .LBB0_434
	s_barrier
